# v9_scan
# speedup vs baseline: 1.0077x; 1.0075x over previous
; DEVI void gla_scan_item(const Params& p, int item) {
;     ...
;   for (int c0 = 0; c0 < 64; c0 += 8) {
;     float4 d[8], dc[8];
; #pragma unroll
;     for (int i = 0; i < 8; ++i) {
;       d[i] = *(const float4*)(dsb + (long)(c0 + i) * 32768);
;       dc[i] = *(const float4*)(dcb + (c0 + i) * 128);
;     }
; #pragma unroll
;     for (int i = 0; i < 8; ++i) {
;       *(bf16x4*)(sb + (long)(c0 + i) * 32768) = pack4(s0, s1, s2, s3);
;       s0 = dc[i].x * s0 + d[i].x;
;       s1 = dc[i].y * s1 + d[i].y;
;       s2 = dc[i].z * s2 + d[i].z;
;       s3 = dc[i].w * s3 + d[i].w;
;     }
;   }
.LBB0_489:
	v_lshl_add_u64 v[50:51], v[2:3], 0, s[12:13]
	v_lshl_add_u64 v[54:55], v[4:5], 0, s[12:13]
	v_lshl_add_u64 v[10:11], v[0:1], 0, s[12:13]
	s_mov_b32 s5, 0x36000000
	v_add_co_u32_e32 v50, vcc, s5, v50
	s_mov_b64 s[8:9], 0x20000
	v_addc_co_u32_e32 v51, vcc, 0, v51, vcc
	s_brev_b32 s5, 52
	v_add_co_u32_e32 v10, vcc, s5, v10
	s_mov_b64 s[4:5], 0x10000
	v_addc_co_u32_e32 v11, vcc, 0, v11, vcc
	global_load_dwordx4 v[64:67], v[50:51], off
	v_lshl_add_u64 v[50:51], v[50:51], 0, s[8:9]
	global_load_dwordx4 v[96:99], v[54:55], off offset:-2048
	global_load_dwordx4 v[68:71], v[50:51], off
	v_lshl_add_u64 v[50:51], v[50:51], 0, s[8:9]
	global_load_dwordx4 v[100:103], v[54:55], off offset:-1536
	global_load_dwordx4 v[72:75], v[50:51], off
	v_lshl_add_u64 v[50:51], v[50:51], 0, s[8:9]
	global_load_dwordx4 v[104:107], v[54:55], off offset:-1024
	global_load_dwordx4 v[76:79], v[50:51], off
	v_lshl_add_u64 v[50:51], v[50:51], 0, s[8:9]
	global_load_dwordx4 v[108:111], v[54:55], off offset:-512
	global_load_dwordx4 v[80:83], v[50:51], off
	v_lshl_add_u64 v[50:51], v[50:51], 0, s[8:9]
	global_load_dwordx4 v[112:115], v[54:55], off
	global_load_dwordx4 v[84:87], v[50:51], off
	v_lshl_add_u64 v[50:51], v[50:51], 0, s[8:9]
	global_load_dwordx4 v[116:119], v[54:55], off offset:512
	global_load_dwordx4 v[88:91], v[50:51], off
	v_lshl_add_u64 v[50:51], v[50:51], 0, s[8:9]
	global_load_dwordx4 v[120:123], v[54:55], off offset:1024
	global_load_dwordx4 v[92:95], v[50:51], off
	v_lshl_add_u64 v[50:51], v[50:51], 0, s[8:9]
	global_load_dwordx4 v[124:127], v[54:55], off offset:1536
	v_lshl_add_u64 v[54:55], v[54:55], 0, s[18:19]
	global_load_dwordx4 v[128:131], v[50:51], off
	v_lshl_add_u64 v[50:51], v[50:51], 0, s[8:9]
	global_load_dwordx4 v[160:163], v[54:55], off offset:-2048
	global_load_dwordx4 v[132:135], v[50:51], off
	v_lshl_add_u64 v[50:51], v[50:51], 0, s[8:9]
	global_load_dwordx4 v[164:167], v[54:55], off offset:-1536
	global_load_dwordx4 v[136:139], v[50:51], off
	v_lshl_add_u64 v[50:51], v[50:51], 0, s[8:9]
	global_load_dwordx4 v[168:171], v[54:55], off offset:-1024
	global_load_dwordx4 v[140:143], v[50:51], off
	v_lshl_add_u64 v[50:51], v[50:51], 0, s[8:9]
	global_load_dwordx4 v[172:175], v[54:55], off offset:-512
	global_load_dwordx4 v[144:147], v[50:51], off
	v_lshl_add_u64 v[50:51], v[50:51], 0, s[8:9]
	global_load_dwordx4 v[176:179], v[54:55], off
	global_load_dwordx4 v[148:151], v[50:51], off
	v_lshl_add_u64 v[50:51], v[50:51], 0, s[8:9]
	global_load_dwordx4 v[180:183], v[54:55], off offset:512
	global_load_dwordx4 v[152:155], v[50:51], off
	v_lshl_add_u64 v[50:51], v[50:51], 0, s[8:9]
	global_load_dwordx4 v[184:187], v[54:55], off offset:1024
	global_load_dwordx4 v[156:159], v[50:51], off
	v_lshl_add_u64 v[50:51], v[50:51], 0, s[8:9]
	global_load_dwordx4 v[188:191], v[54:55], off offset:1536
	v_lshl_add_u64 v[54:55], v[54:55], 0, s[18:19]
	s_waitcnt vmcnt(16)
	v_cvt_pk_bf16_f32 v12, v6, v7
	v_cvt_pk_bf16_f32 v13, v8, v9
	global_store_dwordx2 v[10:11], v[12:13], off
	v_pk_fma_f32 v[6:7], v[6:7], v[96:97], v[64:65]
	v_pk_fma_f32 v[8:9], v[8:9], v[98:99], v[66:67]
	v_lshl_add_u64 v[10:11], v[10:11], 0, s[4:5]
	v_cvt_pk_bf16_f32 v14, v6, v7
	v_cvt_pk_bf16_f32 v15, v8, v9
	global_store_dwordx2 v[10:11], v[14:15], off
	v_pk_fma_f32 v[6:7], v[6:7], v[100:101], v[68:69]
	v_pk_fma_f32 v[8:9], v[8:9], v[102:103], v[70:71]
	v_lshl_add_u64 v[10:11], v[10:11], 0, s[4:5]
	v_cvt_pk_bf16_f32 v16, v6, v7
	v_cvt_pk_bf16_f32 v17, v8, v9
	global_store_dwordx2 v[10:11], v[16:17], off
	v_pk_fma_f32 v[6:7], v[6:7], v[104:105], v[72:73]
	v_pk_fma_f32 v[8:9], v[8:9], v[106:107], v[74:75]
	v_lshl_add_u64 v[10:11], v[10:11], 0, s[4:5]
	v_cvt_pk_bf16_f32 v18, v6, v7
	v_cvt_pk_bf16_f32 v19, v8, v9
	global_store_dwordx2 v[10:11], v[18:19], off
	v_pk_fma_f32 v[6:7], v[6:7], v[108:109], v[76:77]
	v_pk_fma_f32 v[8:9], v[8:9], v[110:111], v[78:79]
	v_lshl_add_u64 v[10:11], v[10:11], 0, s[4:5]
	v_cvt_pk_bf16_f32 v12, v6, v7
	v_cvt_pk_bf16_f32 v13, v8, v9
	global_store_dwordx2 v[10:11], v[12:13], off
	v_pk_fma_f32 v[6:7], v[6:7], v[112:113], v[80:81]
	v_pk_fma_f32 v[8:9], v[8:9], v[114:115], v[82:83]
	v_lshl_add_u64 v[10:11], v[10:11], 0, s[4:5]
	v_cvt_pk_bf16_f32 v14, v6, v7
	v_cvt_pk_bf16_f32 v15, v8, v9
	global_store_dwordx2 v[10:11], v[14:15], off
	v_pk_fma_f32 v[6:7], v[6:7], v[116:117], v[84:85]
	v_pk_fma_f32 v[8:9], v[8:9], v[118:119], v[86:87]
	v_lshl_add_u64 v[10:11], v[10:11], 0, s[4:5]
	v_cvt_pk_bf16_f32 v16, v6, v7
	v_cvt_pk_bf16_f32 v17, v8, v9
	global_store_dwordx2 v[10:11], v[16:17], off
	v_pk_fma_f32 v[6:7], v[6:7], v[120:121], v[88:89]
	v_pk_fma_f32 v[8:9], v[8:9], v[122:123], v[90:91]
	v_lshl_add_u64 v[10:11], v[10:11], 0, s[4:5]
	v_cvt_pk_bf16_f32 v18, v6, v7
	v_cvt_pk_bf16_f32 v19, v8, v9
	global_store_dwordx2 v[10:11], v[18:19], off
	v_pk_fma_f32 v[6:7], v[6:7], v[124:125], v[92:93]
	v_pk_fma_f32 v[8:9], v[8:9], v[126:127], v[94:95]
	v_lshl_add_u64 v[10:11], v[10:11], 0, s[4:5]
	global_load_dwordx4 v[64:67], v[50:51], off
	v_lshl_add_u64 v[50:51], v[50:51], 0, s[8:9]
	global_load_dwordx4 v[96:99], v[54:55], off offset:-2048
	global_load_dwordx4 v[68:71], v[50:51], off
	v_lshl_add_u64 v[50:51], v[50:51], 0, s[8:9]
	global_load_dwordx4 v[100:103], v[54:55], off offset:-1536
	global_load_dwordx4 v[72:75], v[50:51], off
	v_lshl_add_u64 v[50:51], v[50:51], 0, s[8:9]
	global_load_dwordx4 v[104:107], v[54:55], off offset:-1024
	global_load_dwordx4 v[76:79], v[50:51], off
	v_lshl_add_u64 v[50:51], v[50:51], 0, s[8:9]
	global_load_dwordx4 v[108:111], v[54:55], off offset:-512
	global_load_dwordx4 v[80:83], v[50:51], off
	v_lshl_add_u64 v[50:51], v[50:51], 0, s[8:9]
	global_load_dwordx4 v[112:115], v[54:55], off
	global_load_dwordx4 v[84:87], v[50:51], off
	v_lshl_add_u64 v[50:51], v[50:51], 0, s[8:9]
	global_load_dwordx4 v[116:119], v[54:55], off offset:512
	global_load_dwordx4 v[88:91], v[50:51], off
	v_lshl_add_u64 v[50:51], v[50:51], 0, s[8:9]
	global_load_dwordx4 v[120:123], v[54:55], off offset:1024
	global_load_dwordx4 v[92:95], v[50:51], off
	v_lshl_add_u64 v[50:51], v[50:51], 0, s[8:9]
	global_load_dwordx4 v[124:127], v[54:55], off offset:1536
	v_lshl_add_u64 v[54:55], v[54:55], 0, s[18:19]
	s_waitcnt vmcnt(24)
; DEVI void gla_scan_item(const Params& p, int item) {
;     ...
;   for (int c0 = 0; c0 < 64; c0 += 8) {
;     float4 d[8], dc[8];
; #pragma unroll
;     for (int i = 0; i < 8; ++i) {
;       d[i] = *(const float4*)(dsb + (long)(c0 + i) * 32768);
;       dc[i] = *(const float4*)(dcb + (c0 + i) * 128);
;     }
; #pragma unroll
;     for (int i = 0; i < 8; ++i) {
;       *(bf16x4*)(sb + (long)(c0 + i) * 32768) = pack4(s0, s1, s2, s3);
;       s0 = dc[i].x * s0 + d[i].x;
;       s1 = dc[i].y * s1 + d[i].y;
;       s2 = dc[i].z * s2 + d[i].z;
;       s3 = dc[i].w * s3 + d[i].w;
;     }
;   }
	v_cvt_pk_bf16_f32 v12, v6, v7
	v_cvt_pk_bf16_f32 v13, v8, v9
	global_store_dwordx2 v[10:11], v[12:13], off
	v_pk_fma_f32 v[6:7], v[6:7], v[160:161], v[128:129]
	v_pk_fma_f32 v[8:9], v[8:9], v[162:163], v[130:131]
	v_lshl_add_u64 v[10:11], v[10:11], 0, s[4:5]
	v_cvt_pk_bf16_f32 v14, v6, v7
	v_cvt_pk_bf16_f32 v15, v8, v9
	global_store_dwordx2 v[10:11], v[14:15], off
	v_pk_fma_f32 v[6:7], v[6:7], v[164:165], v[132:133]
	v_pk_fma_f32 v[8:9], v[8:9], v[166:167], v[134:135]
	v_lshl_add_u64 v[10:11], v[10:11], 0, s[4:5]
	v_cvt_pk_bf16_f32 v16, v6, v7
	v_cvt_pk_bf16_f32 v17, v8, v9
	global_store_dwordx2 v[10:11], v[16:17], off
	v_pk_fma_f32 v[6:7], v[6:7], v[168:169], v[136:137]
	v_pk_fma_f32 v[8:9], v[8:9], v[170:171], v[138:139]
	v_lshl_add_u64 v[10:11], v[10:11], 0, s[4:5]
	v_cvt_pk_bf16_f32 v18, v6, v7
	v_cvt_pk_bf16_f32 v19, v8, v9
	global_store_dwordx2 v[10:11], v[18:19], off
	v_pk_fma_f32 v[6:7], v[6:7], v[172:173], v[140:141]
	v_pk_fma_f32 v[8:9], v[8:9], v[174:175], v[142:143]
	v_lshl_add_u64 v[10:11], v[10:11], 0, s[4:5]
	v_cvt_pk_bf16_f32 v12, v6, v7
	v_cvt_pk_bf16_f32 v13, v8, v9
	global_store_dwordx2 v[10:11], v[12:13], off
	v_pk_fma_f32 v[6:7], v[6:7], v[176:177], v[144:145]
	v_pk_fma_f32 v[8:9], v[8:9], v[178:179], v[146:147]
	v_lshl_add_u64 v[10:11], v[10:11], 0, s[4:5]
	v_cvt_pk_bf16_f32 v14, v6, v7
	v_cvt_pk_bf16_f32 v15, v8, v9
	global_store_dwordx2 v[10:11], v[14:15], off
	v_pk_fma_f32 v[6:7], v[6:7], v[180:181], v[148:149]
	v_pk_fma_f32 v[8:9], v[8:9], v[182:183], v[150:151]
	v_lshl_add_u64 v[10:11], v[10:11], 0, s[4:5]
	v_cvt_pk_bf16_f32 v16, v6, v7
	v_cvt_pk_bf16_f32 v17, v8, v9
	global_store_dwordx2 v[10:11], v[16:17], off
	v_pk_fma_f32 v[6:7], v[6:7], v[184:185], v[152:153]
	v_pk_fma_f32 v[8:9], v[8:9], v[186:187], v[154:155]
	v_lshl_add_u64 v[10:11], v[10:11], 0, s[4:5]
	v_cvt_pk_bf16_f32 v18, v6, v7
	v_cvt_pk_bf16_f32 v19, v8, v9
	global_store_dwordx2 v[10:11], v[18:19], off
	v_pk_fma_f32 v[6:7], v[6:7], v[188:189], v[156:157]
	v_pk_fma_f32 v[8:9], v[8:9], v[190:191], v[158:159]
	v_lshl_add_u64 v[10:11], v[10:11], 0, s[4:5]
	global_load_dwordx4 v[128:131], v[50:51], off
	v_lshl_add_u64 v[50:51], v[50:51], 0, s[8:9]
	global_load_dwordx4 v[160:163], v[54:55], off offset:-2048
	global_load_dwordx4 v[132:135], v[50:51], off
	v_lshl_add_u64 v[50:51], v[50:51], 0, s[8:9]
	global_load_dwordx4 v[164:167], v[54:55], off offset:-1536
	global_load_dwordx4 v[136:139], v[50:51], off
	v_lshl_add_u64 v[50:51], v[50:51], 0, s[8:9]
	global_load_dwordx4 v[168:171], v[54:55], off offset:-1024
	global_load_dwordx4 v[140:143], v[50:51], off
	v_lshl_add_u64 v[50:51], v[50:51], 0, s[8:9]
	global_load_dwordx4 v[172:175], v[54:55], off offset:-512
	global_load_dwordx4 v[144:147], v[50:51], off
	v_lshl_add_u64 v[50:51], v[50:51], 0, s[8:9]
	global_load_dwordx4 v[176:179], v[54:55], off
	global_load_dwordx4 v[148:151], v[50:51], off
	v_lshl_add_u64 v[50:51], v[50:51], 0, s[8:9]
	global_load_dwordx4 v[180:183], v[54:55], off offset:512
	global_load_dwordx4 v[152:155], v[50:51], off
	v_lshl_add_u64 v[50:51], v[50:51], 0, s[8:9]
	global_load_dwordx4 v[184:187], v[54:55], off offset:1024
	global_load_dwordx4 v[156:159], v[50:51], off
	v_lshl_add_u64 v[50:51], v[50:51], 0, s[8:9]
	global_load_dwordx4 v[188:191], v[54:55], off offset:1536
	v_lshl_add_u64 v[54:55], v[54:55], 0, s[18:19]
	s_waitcnt vmcnt(24)
	v_cvt_pk_bf16_f32 v12, v6, v7
	v_cvt_pk_bf16_f32 v13, v8, v9
	global_store_dwordx2 v[10:11], v[12:13], off
	v_pk_fma_f32 v[6:7], v[6:7], v[96:97], v[64:65]
	v_pk_fma_f32 v[8:9], v[8:9], v[98:99], v[66:67]
	v_lshl_add_u64 v[10:11], v[10:11], 0, s[4:5]
	v_cvt_pk_bf16_f32 v14, v6, v7
	v_cvt_pk_bf16_f32 v15, v8, v9
	global_store_dwordx2 v[10:11], v[14:15], off
	v_pk_fma_f32 v[6:7], v[6:7], v[100:101], v[68:69]
	v_pk_fma_f32 v[8:9], v[8:9], v[102:103], v[70:71]
	v_lshl_add_u64 v[10:11], v[10:11], 0, s[4:5]
	v_cvt_pk_bf16_f32 v16, v6, v7
	v_cvt_pk_bf16_f32 v17, v8, v9
	global_store_dwordx2 v[10:11], v[16:17], off
	v_pk_fma_f32 v[6:7], v[6:7], v[104:105], v[72:73]
	v_pk_fma_f32 v[8:9], v[8:9], v[106:107], v[74:75]
	v_lshl_add_u64 v[10:11], v[10:11], 0, s[4:5]
	v_cvt_pk_bf16_f32 v18, v6, v7
	v_cvt_pk_bf16_f32 v19, v8, v9
	global_store_dwordx2 v[10:11], v[18:19], off
	v_pk_fma_f32 v[6:7], v[6:7], v[108:109], v[76:77]
	v_pk_fma_f32 v[8:9], v[8:9], v[110:111], v[78:79]
	v_lshl_add_u64 v[10:11], v[10:11], 0, s[4:5]
	v_cvt_pk_bf16_f32 v12, v6, v7
	v_cvt_pk_bf16_f32 v13, v8, v9
	global_store_dwordx2 v[10:11], v[12:13], off
	v_pk_fma_f32 v[6:7], v[6:7], v[112:113], v[80:81]
	v_pk_fma_f32 v[8:9], v[8:9], v[114:115], v[82:83]
	v_lshl_add_u64 v[10:11], v[10:11], 0, s[4:5]
	v_cvt_pk_bf16_f32 v14, v6, v7
	v_cvt_pk_bf16_f32 v15, v8, v9
	global_store_dwordx2 v[10:11], v[14:15], off
	v_pk_fma_f32 v[6:7], v[6:7], v[116:117], v[84:85]
	v_pk_fma_f32 v[8:9], v[8:9], v[118:119], v[86:87]
	v_lshl_add_u64 v[10:11], v[10:11], 0, s[4:5]
	v_cvt_pk_bf16_f32 v16, v6, v7
	v_cvt_pk_bf16_f32 v17, v8, v9
	global_store_dwordx2 v[10:11], v[16:17], off
	v_pk_fma_f32 v[6:7], v[6:7], v[120:121], v[88:89]
	v_pk_fma_f32 v[8:9], v[8:9], v[122:123], v[90:91]
	v_lshl_add_u64 v[10:11], v[10:11], 0, s[4:5]
	v_cvt_pk_bf16_f32 v18, v6, v7
	v_cvt_pk_bf16_f32 v19, v8, v9
	global_store_dwordx2 v[10:11], v[18:19], off
	v_pk_fma_f32 v[6:7], v[6:7], v[124:125], v[92:93]
	v_pk_fma_f32 v[8:9], v[8:9], v[126:127], v[94:95]
	v_lshl_add_u64 v[10:11], v[10:11], 0, s[4:5]
	global_load_dwordx4 v[64:67], v[50:51], off
	v_lshl_add_u64 v[50:51], v[50:51], 0, s[8:9]
	global_load_dwordx4 v[96:99], v[54:55], off offset:-2048
	global_load_dwordx4 v[68:71], v[50:51], off
	v_lshl_add_u64 v[50:51], v[50:51], 0, s[8:9]
	global_load_dwordx4 v[100:103], v[54:55], off offset:-1536
	global_load_dwordx4 v[72:75], v[50:51], off
	v_lshl_add_u64 v[50:51], v[50:51], 0, s[8:9]
	global_load_dwordx4 v[104:107], v[54:55], off offset:-1024
	global_load_dwordx4 v[76:79], v[50:51], off
	v_lshl_add_u64 v[50:51], v[50:51], 0, s[8:9]
	global_load_dwordx4 v[108:111], v[54:55], off offset:-512
	global_load_dwordx4 v[80:83], v[50:51], off
	v_lshl_add_u64 v[50:51], v[50:51], 0, s[8:9]
	global_load_dwordx4 v[112:115], v[54:55], off
	global_load_dwordx4 v[84:87], v[50:51], off
	v_lshl_add_u64 v[50:51], v[50:51], 0, s[8:9]
	global_load_dwordx4 v[116:119], v[54:55], off offset:512
	global_load_dwordx4 v[88:91], v[50:51], off
	v_lshl_add_u64 v[50:51], v[50:51], 0, s[8:9]
	global_load_dwordx4 v[120:123], v[54:55], off offset:1024
	global_load_dwordx4 v[92:95], v[50:51], off
	v_lshl_add_u64 v[50:51], v[50:51], 0, s[8:9]
	global_load_dwordx4 v[124:127], v[54:55], off offset:1536
	v_lshl_add_u64 v[54:55], v[54:55], 0, s[18:19]
	s_waitcnt vmcnt(24)
; DEVI void gla_scan_item(const Params& p, int item) {
;     ...
;   for (int c0 = 0; c0 < 64; c0 += 8) {
;     float4 d[8], dc[8];
; #pragma unroll
;     for (int i = 0; i < 8; ++i) {
;       d[i] = *(const float4*)(dsb + (long)(c0 + i) * 32768);
;       dc[i] = *(const float4*)(dcb + (c0 + i) * 128);
;     }
; #pragma unroll
;     for (int i = 0; i < 8; ++i) {
;       *(bf16x4*)(sb + (long)(c0 + i) * 32768) = pack4(s0, s1, s2, s3);
;       s0 = dc[i].x * s0 + d[i].x;
;       s1 = dc[i].y * s1 + d[i].y;
;       s2 = dc[i].z * s2 + d[i].z;
;       s3 = dc[i].w * s3 + d[i].w;
;     }
;   }
	v_cvt_pk_bf16_f32 v12, v6, v7
	v_cvt_pk_bf16_f32 v13, v8, v9
	global_store_dwordx2 v[10:11], v[12:13], off
	v_pk_fma_f32 v[6:7], v[6:7], v[160:161], v[128:129]
	v_pk_fma_f32 v[8:9], v[8:9], v[162:163], v[130:131]
	v_lshl_add_u64 v[10:11], v[10:11], 0, s[4:5]
	v_cvt_pk_bf16_f32 v14, v6, v7
	v_cvt_pk_bf16_f32 v15, v8, v9
	global_store_dwordx2 v[10:11], v[14:15], off
	v_pk_fma_f32 v[6:7], v[6:7], v[164:165], v[132:133]
	v_pk_fma_f32 v[8:9], v[8:9], v[166:167], v[134:135]
	v_lshl_add_u64 v[10:11], v[10:11], 0, s[4:5]
	v_cvt_pk_bf16_f32 v16, v6, v7
	v_cvt_pk_bf16_f32 v17, v8, v9
	global_store_dwordx2 v[10:11], v[16:17], off
	v_pk_fma_f32 v[6:7], v[6:7], v[168:169], v[136:137]
	v_pk_fma_f32 v[8:9], v[8:9], v[170:171], v[138:139]
	v_lshl_add_u64 v[10:11], v[10:11], 0, s[4:5]
	v_cvt_pk_bf16_f32 v18, v6, v7
	v_cvt_pk_bf16_f32 v19, v8, v9
	global_store_dwordx2 v[10:11], v[18:19], off
	v_pk_fma_f32 v[6:7], v[6:7], v[172:173], v[140:141]
	v_pk_fma_f32 v[8:9], v[8:9], v[174:175], v[142:143]
	v_lshl_add_u64 v[10:11], v[10:11], 0, s[4:5]
	v_cvt_pk_bf16_f32 v12, v6, v7
	v_cvt_pk_bf16_f32 v13, v8, v9
	global_store_dwordx2 v[10:11], v[12:13], off
	v_pk_fma_f32 v[6:7], v[6:7], v[176:177], v[144:145]
	v_pk_fma_f32 v[8:9], v[8:9], v[178:179], v[146:147]
	v_lshl_add_u64 v[10:11], v[10:11], 0, s[4:5]
	v_cvt_pk_bf16_f32 v14, v6, v7
	v_cvt_pk_bf16_f32 v15, v8, v9
	global_store_dwordx2 v[10:11], v[14:15], off
	v_pk_fma_f32 v[6:7], v[6:7], v[180:181], v[148:149]
	v_pk_fma_f32 v[8:9], v[8:9], v[182:183], v[150:151]
	v_lshl_add_u64 v[10:11], v[10:11], 0, s[4:5]
	v_cvt_pk_bf16_f32 v16, v6, v7
	v_cvt_pk_bf16_f32 v17, v8, v9
	global_store_dwordx2 v[10:11], v[16:17], off
	v_pk_fma_f32 v[6:7], v[6:7], v[184:185], v[152:153]
	v_pk_fma_f32 v[8:9], v[8:9], v[186:187], v[154:155]
	v_lshl_add_u64 v[10:11], v[10:11], 0, s[4:5]
	v_cvt_pk_bf16_f32 v18, v6, v7
	v_cvt_pk_bf16_f32 v19, v8, v9
	global_store_dwordx2 v[10:11], v[18:19], off
	v_pk_fma_f32 v[6:7], v[6:7], v[188:189], v[156:157]
	v_pk_fma_f32 v[8:9], v[8:9], v[190:191], v[158:159]
	v_lshl_add_u64 v[10:11], v[10:11], 0, s[4:5]
	global_load_dwordx4 v[128:131], v[50:51], off
	v_lshl_add_u64 v[50:51], v[50:51], 0, s[8:9]
	global_load_dwordx4 v[160:163], v[54:55], off offset:-2048
	global_load_dwordx4 v[132:135], v[50:51], off
	v_lshl_add_u64 v[50:51], v[50:51], 0, s[8:9]
	global_load_dwordx4 v[164:167], v[54:55], off offset:-1536
	global_load_dwordx4 v[136:139], v[50:51], off
	v_lshl_add_u64 v[50:51], v[50:51], 0, s[8:9]
	global_load_dwordx4 v[168:171], v[54:55], off offset:-1024
	global_load_dwordx4 v[140:143], v[50:51], off
	v_lshl_add_u64 v[50:51], v[50:51], 0, s[8:9]
	global_load_dwordx4 v[172:175], v[54:55], off offset:-512
	global_load_dwordx4 v[144:147], v[50:51], off
	v_lshl_add_u64 v[50:51], v[50:51], 0, s[8:9]
	global_load_dwordx4 v[176:179], v[54:55], off
	global_load_dwordx4 v[148:151], v[50:51], off
	v_lshl_add_u64 v[50:51], v[50:51], 0, s[8:9]
	global_load_dwordx4 v[180:183], v[54:55], off offset:512
	global_load_dwordx4 v[152:155], v[50:51], off
	v_lshl_add_u64 v[50:51], v[50:51], 0, s[8:9]
	global_load_dwordx4 v[184:187], v[54:55], off offset:1024
	global_load_dwordx4 v[156:159], v[50:51], off
	v_lshl_add_u64 v[50:51], v[50:51], 0, s[8:9]
	global_load_dwordx4 v[188:191], v[54:55], off offset:1536
	v_lshl_add_u64 v[54:55], v[54:55], 0, s[18:19]
	s_waitcnt vmcnt(24)
	v_cvt_pk_bf16_f32 v12, v6, v7
	v_cvt_pk_bf16_f32 v13, v8, v9
	global_store_dwordx2 v[10:11], v[12:13], off
	v_pk_fma_f32 v[6:7], v[6:7], v[96:97], v[64:65]
	v_pk_fma_f32 v[8:9], v[8:9], v[98:99], v[66:67]
	v_lshl_add_u64 v[10:11], v[10:11], 0, s[4:5]
	v_cvt_pk_bf16_f32 v14, v6, v7
	v_cvt_pk_bf16_f32 v15, v8, v9
	global_store_dwordx2 v[10:11], v[14:15], off
	v_pk_fma_f32 v[6:7], v[6:7], v[100:101], v[68:69]
	v_pk_fma_f32 v[8:9], v[8:9], v[102:103], v[70:71]
	v_lshl_add_u64 v[10:11], v[10:11], 0, s[4:5]
	v_cvt_pk_bf16_f32 v16, v6, v7
	v_cvt_pk_bf16_f32 v17, v8, v9
	global_store_dwordx2 v[10:11], v[16:17], off
	v_pk_fma_f32 v[6:7], v[6:7], v[104:105], v[72:73]
	v_pk_fma_f32 v[8:9], v[8:9], v[106:107], v[74:75]
	v_lshl_add_u64 v[10:11], v[10:11], 0, s[4:5]
	v_cvt_pk_bf16_f32 v18, v6, v7
	v_cvt_pk_bf16_f32 v19, v8, v9
	global_store_dwordx2 v[10:11], v[18:19], off
	v_pk_fma_f32 v[6:7], v[6:7], v[108:109], v[76:77]
	v_pk_fma_f32 v[8:9], v[8:9], v[110:111], v[78:79]
	v_lshl_add_u64 v[10:11], v[10:11], 0, s[4:5]
	v_cvt_pk_bf16_f32 v12, v6, v7
	v_cvt_pk_bf16_f32 v13, v8, v9
	global_store_dwordx2 v[10:11], v[12:13], off
	v_pk_fma_f32 v[6:7], v[6:7], v[112:113], v[80:81]
	v_pk_fma_f32 v[8:9], v[8:9], v[114:115], v[82:83]
	v_lshl_add_u64 v[10:11], v[10:11], 0, s[4:5]
	v_cvt_pk_bf16_f32 v14, v6, v7
	v_cvt_pk_bf16_f32 v15, v8, v9
	global_store_dwordx2 v[10:11], v[14:15], off
	v_pk_fma_f32 v[6:7], v[6:7], v[116:117], v[84:85]
	v_pk_fma_f32 v[8:9], v[8:9], v[118:119], v[86:87]
	v_lshl_add_u64 v[10:11], v[10:11], 0, s[4:5]
	v_cvt_pk_bf16_f32 v16, v6, v7
	v_cvt_pk_bf16_f32 v17, v8, v9
	global_store_dwordx2 v[10:11], v[16:17], off
	v_pk_fma_f32 v[6:7], v[6:7], v[120:121], v[88:89]
	v_pk_fma_f32 v[8:9], v[8:9], v[122:123], v[90:91]
	v_lshl_add_u64 v[10:11], v[10:11], 0, s[4:5]
	v_cvt_pk_bf16_f32 v18, v6, v7
	v_cvt_pk_bf16_f32 v19, v8, v9
	global_store_dwordx2 v[10:11], v[18:19], off
	v_pk_fma_f32 v[6:7], v[6:7], v[124:125], v[92:93]
	v_pk_fma_f32 v[8:9], v[8:9], v[126:127], v[94:95]
	v_lshl_add_u64 v[10:11], v[10:11], 0, s[4:5]
	global_load_dwordx4 v[64:67], v[50:51], off
	v_lshl_add_u64 v[50:51], v[50:51], 0, s[8:9]
	global_load_dwordx4 v[96:99], v[54:55], off offset:-2048
	global_load_dwordx4 v[68:71], v[50:51], off
	v_lshl_add_u64 v[50:51], v[50:51], 0, s[8:9]
	global_load_dwordx4 v[100:103], v[54:55], off offset:-1536
	global_load_dwordx4 v[72:75], v[50:51], off
	v_lshl_add_u64 v[50:51], v[50:51], 0, s[8:9]
	global_load_dwordx4 v[104:107], v[54:55], off offset:-1024
	global_load_dwordx4 v[76:79], v[50:51], off
	v_lshl_add_u64 v[50:51], v[50:51], 0, s[8:9]
	global_load_dwordx4 v[108:111], v[54:55], off offset:-512
	global_load_dwordx4 v[80:83], v[50:51], off
	v_lshl_add_u64 v[50:51], v[50:51], 0, s[8:9]
	global_load_dwordx4 v[112:115], v[54:55], off
	global_load_dwordx4 v[84:87], v[50:51], off
	v_lshl_add_u64 v[50:51], v[50:51], 0, s[8:9]
	global_load_dwordx4 v[116:119], v[54:55], off offset:512
	global_load_dwordx4 v[88:91], v[50:51], off
	v_lshl_add_u64 v[50:51], v[50:51], 0, s[8:9]
	global_load_dwordx4 v[120:123], v[54:55], off offset:1024
	global_load_dwordx4 v[92:95], v[50:51], off
	v_lshl_add_u64 v[50:51], v[50:51], 0, s[8:9]
	global_load_dwordx4 v[124:127], v[54:55], off offset:1536
	v_lshl_add_u64 v[54:55], v[54:55], 0, s[18:19]
	s_waitcnt vmcnt(24)
; DEVI void gla_scan_item(const Params& p, int item) {
;     ...
;   for (int c0 = 0; c0 < 64; c0 += 8) {
;     float4 d[8], dc[8];
; #pragma unroll
;     for (int i = 0; i < 8; ++i) {
;       d[i] = *(const float4*)(dsb + (long)(c0 + i) * 32768);
;       dc[i] = *(const float4*)(dcb + (c0 + i) * 128);
;     }
; #pragma unroll
;     for (int i = 0; i < 8; ++i) {
;       *(bf16x4*)(sb + (long)(c0 + i) * 32768) = pack4(s0, s1, s2, s3);
;       s0 = dc[i].x * s0 + d[i].x;
;       s1 = dc[i].y * s1 + d[i].y;
;       s2 = dc[i].z * s2 + d[i].z;
;       s3 = dc[i].w * s3 + d[i].w;
;     }
;   }
	v_cvt_pk_bf16_f32 v12, v6, v7
	v_cvt_pk_bf16_f32 v13, v8, v9
	global_store_dwordx2 v[10:11], v[12:13], off
	v_pk_fma_f32 v[6:7], v[6:7], v[160:161], v[128:129]
	v_pk_fma_f32 v[8:9], v[8:9], v[162:163], v[130:131]
	v_lshl_add_u64 v[10:11], v[10:11], 0, s[4:5]
	v_cvt_pk_bf16_f32 v14, v6, v7
	v_cvt_pk_bf16_f32 v15, v8, v9
	global_store_dwordx2 v[10:11], v[14:15], off
	v_pk_fma_f32 v[6:7], v[6:7], v[164:165], v[132:133]
	v_pk_fma_f32 v[8:9], v[8:9], v[166:167], v[134:135]
	v_lshl_add_u64 v[10:11], v[10:11], 0, s[4:5]
	v_cvt_pk_bf16_f32 v16, v6, v7
	v_cvt_pk_bf16_f32 v17, v8, v9
	global_store_dwordx2 v[10:11], v[16:17], off
	v_pk_fma_f32 v[6:7], v[6:7], v[168:169], v[136:137]
	v_pk_fma_f32 v[8:9], v[8:9], v[170:171], v[138:139]
	v_lshl_add_u64 v[10:11], v[10:11], 0, s[4:5]
	v_cvt_pk_bf16_f32 v18, v6, v7
	v_cvt_pk_bf16_f32 v19, v8, v9
	global_store_dwordx2 v[10:11], v[18:19], off
	v_pk_fma_f32 v[6:7], v[6:7], v[172:173], v[140:141]
	v_pk_fma_f32 v[8:9], v[8:9], v[174:175], v[142:143]
	v_lshl_add_u64 v[10:11], v[10:11], 0, s[4:5]
	v_cvt_pk_bf16_f32 v12, v6, v7
	v_cvt_pk_bf16_f32 v13, v8, v9
	global_store_dwordx2 v[10:11], v[12:13], off
	v_pk_fma_f32 v[6:7], v[6:7], v[176:177], v[144:145]
	v_pk_fma_f32 v[8:9], v[8:9], v[178:179], v[146:147]
	v_lshl_add_u64 v[10:11], v[10:11], 0, s[4:5]
	v_cvt_pk_bf16_f32 v14, v6, v7
	v_cvt_pk_bf16_f32 v15, v8, v9
	global_store_dwordx2 v[10:11], v[14:15], off
	v_pk_fma_f32 v[6:7], v[6:7], v[180:181], v[148:149]
	v_pk_fma_f32 v[8:9], v[8:9], v[182:183], v[150:151]
	v_lshl_add_u64 v[10:11], v[10:11], 0, s[4:5]
	v_cvt_pk_bf16_f32 v16, v6, v7
	v_cvt_pk_bf16_f32 v17, v8, v9
	global_store_dwordx2 v[10:11], v[16:17], off
	v_pk_fma_f32 v[6:7], v[6:7], v[184:185], v[152:153]
	v_pk_fma_f32 v[8:9], v[8:9], v[186:187], v[154:155]
	v_lshl_add_u64 v[10:11], v[10:11], 0, s[4:5]
	v_cvt_pk_bf16_f32 v18, v6, v7
	v_cvt_pk_bf16_f32 v19, v8, v9
	global_store_dwordx2 v[10:11], v[18:19], off
	v_pk_fma_f32 v[6:7], v[6:7], v[188:189], v[156:157]
	v_pk_fma_f32 v[8:9], v[8:9], v[190:191], v[158:159]
	v_lshl_add_u64 v[10:11], v[10:11], 0, s[4:5]
	global_load_dwordx4 v[128:131], v[50:51], off
	v_lshl_add_u64 v[50:51], v[50:51], 0, s[8:9]
	global_load_dwordx4 v[160:163], v[54:55], off offset:-2048
	global_load_dwordx4 v[132:135], v[50:51], off
	v_lshl_add_u64 v[50:51], v[50:51], 0, s[8:9]
	global_load_dwordx4 v[164:167], v[54:55], off offset:-1536
	global_load_dwordx4 v[136:139], v[50:51], off
	v_lshl_add_u64 v[50:51], v[50:51], 0, s[8:9]
	global_load_dwordx4 v[168:171], v[54:55], off offset:-1024
	global_load_dwordx4 v[140:143], v[50:51], off
	v_lshl_add_u64 v[50:51], v[50:51], 0, s[8:9]
	global_load_dwordx4 v[172:175], v[54:55], off offset:-512
	global_load_dwordx4 v[144:147], v[50:51], off
	v_lshl_add_u64 v[50:51], v[50:51], 0, s[8:9]
	global_load_dwordx4 v[176:179], v[54:55], off
	global_load_dwordx4 v[148:151], v[50:51], off
	v_lshl_add_u64 v[50:51], v[50:51], 0, s[8:9]
	global_load_dwordx4 v[180:183], v[54:55], off offset:512
	global_load_dwordx4 v[152:155], v[50:51], off
	v_lshl_add_u64 v[50:51], v[50:51], 0, s[8:9]
	global_load_dwordx4 v[184:187], v[54:55], off offset:1024
	global_load_dwordx4 v[156:159], v[50:51], off
	v_lshl_add_u64 v[50:51], v[50:51], 0, s[8:9]
	global_load_dwordx4 v[188:191], v[54:55], off offset:1536
	v_lshl_add_u64 v[54:55], v[54:55], 0, s[18:19]
	s_waitcnt vmcnt(24)
; DEVI void gla_scan_item(const Params& p, int item) {
;     ...
;   for (int c0 = 0; c0 < 64; c0 += 8) {
;     float4 d[8], dc[8];
; #pragma unroll
;     for (int i = 0; i < 8; ++i) {
;       d[i] = *(const float4*)(dsb + (long)(c0 + i) * 32768);
;       dc[i] = *(const float4*)(dcb + (c0 + i) * 128);
;     }
; #pragma unroll
;     for (int i = 0; i < 8; ++i) {
;       *(bf16x4*)(sb + (long)(c0 + i) * 32768) = pack4(s0, s1, s2, s3);
;       s0 = dc[i].x * s0 + d[i].x;
;       s1 = dc[i].y * s1 + d[i].y;
;       s2 = dc[i].z * s2 + d[i].z;
;       s3 = dc[i].w * s3 + d[i].w;
;     }
;   }
	v_cvt_pk_bf16_f32 v12, v6, v7
	v_cvt_pk_bf16_f32 v13, v8, v9
	global_store_dwordx2 v[10:11], v[12:13], off
	v_pk_fma_f32 v[6:7], v[6:7], v[96:97], v[64:65]
	v_pk_fma_f32 v[8:9], v[8:9], v[98:99], v[66:67]
	v_lshl_add_u64 v[10:11], v[10:11], 0, s[4:5]
	v_cvt_pk_bf16_f32 v14, v6, v7
	v_cvt_pk_bf16_f32 v15, v8, v9
	global_store_dwordx2 v[10:11], v[14:15], off
	v_pk_fma_f32 v[6:7], v[6:7], v[100:101], v[68:69]
	v_pk_fma_f32 v[8:9], v[8:9], v[102:103], v[70:71]
	v_lshl_add_u64 v[10:11], v[10:11], 0, s[4:5]
	v_cvt_pk_bf16_f32 v16, v6, v7
	v_cvt_pk_bf16_f32 v17, v8, v9
	global_store_dwordx2 v[10:11], v[16:17], off
	v_pk_fma_f32 v[6:7], v[6:7], v[104:105], v[72:73]
	v_pk_fma_f32 v[8:9], v[8:9], v[106:107], v[74:75]
	v_lshl_add_u64 v[10:11], v[10:11], 0, s[4:5]
	v_cvt_pk_bf16_f32 v18, v6, v7
	v_cvt_pk_bf16_f32 v19, v8, v9
	global_store_dwordx2 v[10:11], v[18:19], off
	v_pk_fma_f32 v[6:7], v[6:7], v[108:109], v[76:77]
	v_pk_fma_f32 v[8:9], v[8:9], v[110:111], v[78:79]
	v_lshl_add_u64 v[10:11], v[10:11], 0, s[4:5]
	v_cvt_pk_bf16_f32 v12, v6, v7
	v_cvt_pk_bf16_f32 v13, v8, v9
	global_store_dwordx2 v[10:11], v[12:13], off
	v_pk_fma_f32 v[6:7], v[6:7], v[112:113], v[80:81]
	v_pk_fma_f32 v[8:9], v[8:9], v[114:115], v[82:83]
	v_lshl_add_u64 v[10:11], v[10:11], 0, s[4:5]
	v_cvt_pk_bf16_f32 v14, v6, v7
	v_cvt_pk_bf16_f32 v15, v8, v9
	global_store_dwordx2 v[10:11], v[14:15], off
	v_pk_fma_f32 v[6:7], v[6:7], v[116:117], v[84:85]
	v_pk_fma_f32 v[8:9], v[8:9], v[118:119], v[86:87]
	v_lshl_add_u64 v[10:11], v[10:11], 0, s[4:5]
	v_cvt_pk_bf16_f32 v16, v6, v7
	v_cvt_pk_bf16_f32 v17, v8, v9
	global_store_dwordx2 v[10:11], v[16:17], off
	v_pk_fma_f32 v[6:7], v[6:7], v[120:121], v[88:89]
	v_pk_fma_f32 v[8:9], v[8:9], v[122:123], v[90:91]
	v_lshl_add_u64 v[10:11], v[10:11], 0, s[4:5]
	v_cvt_pk_bf16_f32 v18, v6, v7
	v_cvt_pk_bf16_f32 v19, v8, v9
	global_store_dwordx2 v[10:11], v[18:19], off
	v_pk_fma_f32 v[6:7], v[6:7], v[124:125], v[92:93]
	v_pk_fma_f32 v[8:9], v[8:9], v[126:127], v[94:95]
	v_lshl_add_u64 v[10:11], v[10:11], 0, s[4:5]
	s_waitcnt vmcnt(8)
	v_cvt_pk_bf16_f32 v12, v6, v7
	v_cvt_pk_bf16_f32 v13, v8, v9
	global_store_dwordx2 v[10:11], v[12:13], off
	v_pk_fma_f32 v[6:7], v[6:7], v[160:161], v[128:129]
	v_pk_fma_f32 v[8:9], v[8:9], v[162:163], v[130:131]
	v_lshl_add_u64 v[10:11], v[10:11], 0, s[4:5]
	v_cvt_pk_bf16_f32 v14, v6, v7
	v_cvt_pk_bf16_f32 v15, v8, v9
	global_store_dwordx2 v[10:11], v[14:15], off
	v_pk_fma_f32 v[6:7], v[6:7], v[164:165], v[132:133]
	v_pk_fma_f32 v[8:9], v[8:9], v[166:167], v[134:135]
	v_lshl_add_u64 v[10:11], v[10:11], 0, s[4:5]
	v_cvt_pk_bf16_f32 v16, v6, v7
	v_cvt_pk_bf16_f32 v17, v8, v9
	global_store_dwordx2 v[10:11], v[16:17], off
	v_pk_fma_f32 v[6:7], v[6:7], v[168:169], v[136:137]
	v_pk_fma_f32 v[8:9], v[8:9], v[170:171], v[138:139]
	v_lshl_add_u64 v[10:11], v[10:11], 0, s[4:5]
	v_cvt_pk_bf16_f32 v18, v6, v7
	v_cvt_pk_bf16_f32 v19, v8, v9
	global_store_dwordx2 v[10:11], v[18:19], off
	v_pk_fma_f32 v[6:7], v[6:7], v[172:173], v[140:141]
	v_pk_fma_f32 v[8:9], v[8:9], v[174:175], v[142:143]
	v_lshl_add_u64 v[10:11], v[10:11], 0, s[4:5]
	v_cvt_pk_bf16_f32 v12, v6, v7
	v_cvt_pk_bf16_f32 v13, v8, v9
	global_store_dwordx2 v[10:11], v[12:13], off
	v_pk_fma_f32 v[6:7], v[6:7], v[176:177], v[144:145]
	v_pk_fma_f32 v[8:9], v[8:9], v[178:179], v[146:147]
	v_lshl_add_u64 v[10:11], v[10:11], 0, s[4:5]
	v_cvt_pk_bf16_f32 v14, v6, v7
	v_cvt_pk_bf16_f32 v15, v8, v9
	global_store_dwordx2 v[10:11], v[14:15], off
	v_pk_fma_f32 v[6:7], v[6:7], v[180:181], v[148:149]
	v_pk_fma_f32 v[8:9], v[8:9], v[182:183], v[150:151]
	v_lshl_add_u64 v[10:11], v[10:11], 0, s[4:5]
	v_cvt_pk_bf16_f32 v16, v6, v7
	v_cvt_pk_bf16_f32 v17, v8, v9
	global_store_dwordx2 v[10:11], v[16:17], off
	v_pk_fma_f32 v[6:7], v[6:7], v[184:185], v[152:153]
	v_pk_fma_f32 v[8:9], v[8:9], v[186:187], v[154:155]
	v_lshl_add_u64 v[10:11], v[10:11], 0, s[4:5]
	v_cvt_pk_bf16_f32 v18, v6, v7
	v_cvt_pk_bf16_f32 v19, v8, v9
	global_store_dwordx2 v[10:11], v[18:19], off
	v_pk_fma_f32 v[6:7], v[6:7], v[188:189], v[156:157]
	v_pk_fma_f32 v[8:9], v[8:9], v[190:191], v[158:159]
	v_lshl_add_u64 v[10:11], v[10:11], 0, s[4:5]

; DEVI float bfs(short h) { return __uint_as_float(((unsigned)(u16)h) << 16); }
; DEVI void moba_item(const Params& p, int l, int item) {
;     ...
;   for (int i = 0; i < 4; ++i) {
;     int ch = tid + i * 512;
;     int row = ch >> 4, dg = ch & 15;
;     *(bf16x8*)(Qs + row * 136 + dg * 8) = *(const bf16x8*)(proj + (t0 + row) * NP + C_CQ + h * 128 + dg * 8);
;   }
;   for (int i = tid; i < qblk * 128; i += 512) km[i] = p.kmean[(long)(bh * 16) * 128 + i];
;   if (tid == 0) selm[128] = 0u;
;   __syncthreads();
;   {
;     const int q = tid & 127, part = tid >> 7;
;     float dots[4] = {0.f, 0.f, 0.f, 0.f};
; #pragma unroll
;     for (int c = 0; c < 16; ++c) {
;       const bf16x8 qv = *(const bf16x8*)(Qs + q * 136 + c * 8);
;       float qf[8];
; #pragma unroll
;       for (int e = 0; e < 8; ++e) qf[e] = bfs(qv[e]);
; #pragma unroll
;       for (int k = 0; k < 4; ++k) {
;         const int blk = part + 4 * k;
;         if (blk < qblk) {
; #pragma unroll
;           for (int e = 0; e < 8; ++e) dots[k] += qf[e] * km[blk * 128 + c * 8 + e];
;         }
;       }
;     }
.LBB0_502:
	s_or_b64 exec, exec, s[2:3]
	s_waitcnt vmcnt(0)
	ds_write_b128 v196, v[180:183]
	ds_write_b128 v196, v[184:187] offset:8704
	ds_write_b128 v196, v[188:191] offset:17408
	ds_write_b128 v196, v[192:195] offset:26112
	v_cmp_eq_u32_e32 vcc, 0, v48
	s_and_saveexec_b64 s[2:3], vcc
	v_mov_b32_e32 v32, s73
	ds_write_b32 v32, v211
	s_or_b64 exec, exec, s[2:3]
	v_and_b32_e32 v40, 0x7f, v48
	v_mad_u32_u24 v32, v40, s71, 0
	v_add_u32_e32 v32, 0x11800, v32
	s_waitcnt lgkmcnt(0)
	s_barrier
	v_lshrrev_b32_e32 v35, 7, v48
	v_mov_b32_e32 v36, 0
	v_readfirstlane_b32 s2, v35
	s_sub_i32 s3, s28, s2
	s_add_i32 s3, s3, 3
	s_ashr_i32 s3, s3, 2
	s_cmp_lt_i32 s3, 1
	s_cbranch_scc1 .Lmy_gd_done
	v_lshl_add_u32 v33, v35, 9, s72
	v_mov_b32_e32 v37, 0
	v_mov_b32_e32 v38, 0
	v_mov_b32_e32 v39, 0
	ds_read_b128 v[56:59], v32
	ds_read_b128 v[60:63], v33
	ds_read_b128 v[64:67], v33 offset:16
	ds_read_b128 v[68:71], v33 offset:2048
	ds_read_b128 v[72:75], v33 offset:2064
	ds_read_b128 v[76:79], v33 offset:4096
	ds_read_b128 v[80:83], v33 offset:4112
	ds_read_b128 v[84:87], v33 offset:6144
	ds_read_b128 v[88:91], v33 offset:6160
	ds_read_b128 v[92:95], v32 offset:16
	ds_read_b128 v[96:99], v33 offset:32
	ds_read_b128 v[100:103], v33 offset:48
	ds_read_b128 v[104:107], v33 offset:2080
	ds_read_b128 v[108:111], v33 offset:2096
	ds_read_b128 v[112:115], v33 offset:4128
	ds_read_b128 v[116:119], v33 offset:4144
	ds_read_b128 v[120:123], v33 offset:6176
	ds_read_b128 v[124:127], v33 offset:6192
	s_waitcnt lgkmcnt(9)
	v_lshlrev_b32_e32 v128, 16, v56
	v_and_b32_e32 v129, 0xffff0000, v56
	v_lshlrev_b32_e32 v130, 16, v57
	v_and_b32_e32 v131, 0xffff0000, v57
	v_lshlrev_b32_e32 v132, 16, v58
	v_and_b32_e32 v133, 0xffff0000, v58
	v_lshlrev_b32_e32 v134, 16, v59
	v_and_b32_e32 v135, 0xffff0000, v59
	v_pk_mul_f32 v[136:137], v[60:61], v[128:129]
	v_pk_mul_f32 v[138:139], v[62:63], v[130:131]
	v_pk_mul_f32 v[140:141], v[64:65], v[132:133]
	v_pk_mul_f32 v[142:143], v[66:67], v[134:135]
	v_add_f32_e32 v36, v36, v136
	v_add_f32_e32 v36, v36, v137
	v_add_f32_e32 v36, v36, v138
	v_add_f32_e32 v36, v36, v139
	v_add_f32_e32 v36, v36, v140
	v_add_f32_e32 v36, v36, v141
	v_add_f32_e32 v36, v36, v142
	v_add_f32_e32 v36, v36, v143
	s_cmp_lt_i32 s3, 2
	s_cbranch_scc1 .Lmy_gd_c0
	v_pk_mul_f32 v[136:137], v[68:69], v[128:129]
	v_pk_mul_f32 v[138:139], v[70:71], v[130:131]
	v_pk_mul_f32 v[140:141], v[72:73], v[132:133]
	v_pk_mul_f32 v[142:143], v[74:75], v[134:135]
	v_add_f32_e32 v37, v37, v136
	v_add_f32_e32 v37, v37, v137
	v_add_f32_e32 v37, v37, v138
	v_add_f32_e32 v37, v37, v139
	v_add_f32_e32 v37, v37, v140
	v_add_f32_e32 v37, v37, v141
	v_add_f32_e32 v37, v37, v142
	v_add_f32_e32 v37, v37, v143
	s_cmp_lt_i32 s3, 3
	s_cbranch_scc1 .Lmy_gd_c0
	v_pk_mul_f32 v[136:137], v[76:77], v[128:129]
	v_pk_mul_f32 v[138:139], v[78:79], v[130:131]
	v_pk_mul_f32 v[140:141], v[80:81], v[132:133]
	v_pk_mul_f32 v[142:143], v[82:83], v[134:135]
	v_add_f32_e32 v38, v38, v136
	v_add_f32_e32 v38, v38, v137
	v_add_f32_e32 v38, v38, v138
	v_add_f32_e32 v38, v38, v139
	v_add_f32_e32 v38, v38, v140
	v_add_f32_e32 v38, v38, v141
	v_add_f32_e32 v38, v38, v142
	v_add_f32_e32 v38, v38, v143
	s_cmp_lt_i32 s3, 4
	s_cbranch_scc1 .Lmy_gd_c0
	v_pk_mul_f32 v[136:137], v[84:85], v[128:129]
	v_pk_mul_f32 v[138:139], v[86:87], v[130:131]
	v_pk_mul_f32 v[140:141], v[88:89], v[132:133]
	v_pk_mul_f32 v[142:143], v[90:91], v[134:135]
	v_add_f32_e32 v39, v39, v136
	v_add_f32_e32 v39, v39, v137
	v_add_f32_e32 v39, v39, v138
	v_add_f32_e32 v39, v39, v139
	v_add_f32_e32 v39, v39, v140
	v_add_f32_e32 v39, v39, v141
	v_add_f32_e32 v39, v39, v142
	v_add_f32_e32 v39, v39, v143
.Lmy_gd_c0:
	ds_read_b128 v[56:59], v32 offset:32
	ds_read_b128 v[60:63], v33 offset:64
	ds_read_b128 v[64:67], v33 offset:80
	ds_read_b128 v[68:71], v33 offset:2112
	ds_read_b128 v[72:75], v33 offset:2128
	ds_read_b128 v[76:79], v33 offset:4160
	ds_read_b128 v[80:83], v33 offset:4176
	ds_read_b128 v[84:87], v33 offset:6208
	ds_read_b128 v[88:91], v33 offset:6224
	s_waitcnt lgkmcnt(9)
	v_lshlrev_b32_e32 v128, 16, v92
	v_and_b32_e32 v129, 0xffff0000, v92
	v_lshlrev_b32_e32 v130, 16, v93
	v_and_b32_e32 v131, 0xffff0000, v93
	v_lshlrev_b32_e32 v132, 16, v94
	v_and_b32_e32 v133, 0xffff0000, v94
	v_lshlrev_b32_e32 v134, 16, v95
	v_and_b32_e32 v135, 0xffff0000, v95
	v_pk_mul_f32 v[136:137], v[96:97], v[128:129]
	v_pk_mul_f32 v[138:139], v[98:99], v[130:131]
	v_pk_mul_f32 v[140:141], v[100:101], v[132:133]
	v_pk_mul_f32 v[142:143], v[102:103], v[134:135]
	v_add_f32_e32 v36, v36, v136
	v_add_f32_e32 v36, v36, v137
	v_add_f32_e32 v36, v36, v138
	v_add_f32_e32 v36, v36, v139
	v_add_f32_e32 v36, v36, v140
	v_add_f32_e32 v36, v36, v141
	v_add_f32_e32 v36, v36, v142
	v_add_f32_e32 v36, v36, v143
	s_cmp_lt_i32 s3, 2
	s_cbranch_scc1 .Lmy_gd_c1
	v_pk_mul_f32 v[136:137], v[104:105], v[128:129]
	v_pk_mul_f32 v[138:139], v[106:107], v[130:131]
	v_pk_mul_f32 v[140:141], v[108:109], v[132:133]
	v_pk_mul_f32 v[142:143], v[110:111], v[134:135]
	v_add_f32_e32 v37, v37, v136
	v_add_f32_e32 v37, v37, v137
	v_add_f32_e32 v37, v37, v138
	v_add_f32_e32 v37, v37, v139
	v_add_f32_e32 v37, v37, v140
	v_add_f32_e32 v37, v37, v141
	v_add_f32_e32 v37, v37, v142
	v_add_f32_e32 v37, v37, v143
	s_cmp_lt_i32 s3, 3
	s_cbranch_scc1 .Lmy_gd_c1
	v_pk_mul_f32 v[136:137], v[112:113], v[128:129]
	v_pk_mul_f32 v[138:139], v[114:115], v[130:131]
	v_pk_mul_f32 v[140:141], v[116:117], v[132:133]
	v_pk_mul_f32 v[142:143], v[118:119], v[134:135]
	v_add_f32_e32 v38, v38, v136
	v_add_f32_e32 v38, v38, v137
	v_add_f32_e32 v38, v38, v138
	v_add_f32_e32 v38, v38, v139
	v_add_f32_e32 v38, v38, v140
	v_add_f32_e32 v38, v38, v141
	v_add_f32_e32 v38, v38, v142
	v_add_f32_e32 v38, v38, v143
	s_cmp_lt_i32 s3, 4
	s_cbranch_scc1 .Lmy_gd_c1
	v_pk_mul_f32 v[136:137], v[120:121], v[128:129]
	v_pk_mul_f32 v[138:139], v[122:123], v[130:131]
	v_pk_mul_f32 v[140:141], v[124:125], v[132:133]
	v_pk_mul_f32 v[142:143], v[126:127], v[134:135]
	v_add_f32_e32 v39, v39, v136
	v_add_f32_e32 v39, v39, v137
	v_add_f32_e32 v39, v39, v138
	v_add_f32_e32 v39, v39, v139
	v_add_f32_e32 v39, v39, v140
	v_add_f32_e32 v39, v39, v141
	v_add_f32_e32 v39, v39, v142
	v_add_f32_e32 v39, v39, v143
; DEVI float bfs(short h) { return __uint_as_float(((unsigned)(u16)h) << 16); }
; DEVI void moba_item(const Params& p, int l, int item) {
;     ...
; #pragma unroll
;     for (int c = 0; c < 16; ++c) {
;       const bf16x8 qv = *(const bf16x8*)(Qs + q * 136 + c * 8);
;       float qf[8];
; #pragma unroll
;       for (int e = 0; e < 8; ++e) qf[e] = bfs(qv[e]);
; #pragma unroll
;       for (int k = 0; k < 4; ++k) {
;         const int blk = part + 4 * k;
;         if (blk < qblk) {
; #pragma unroll
;           for (int e = 0; e < 8; ++e) dots[k] += qf[e] * km[blk * 128 + c * 8 + e];
;         }
;       }
;     }
.Lmy_gd_c1:
	ds_read_b128 v[92:95], v32 offset:48
	ds_read_b128 v[96:99], v33 offset:96
	ds_read_b128 v[100:103], v33 offset:112
	ds_read_b128 v[104:107], v33 offset:2144
	ds_read_b128 v[108:111], v33 offset:2160
	ds_read_b128 v[112:115], v33 offset:4192
	ds_read_b128 v[116:119], v33 offset:4208
	ds_read_b128 v[120:123], v33 offset:6240
	ds_read_b128 v[124:127], v33 offset:6256
	s_waitcnt lgkmcnt(9)
	v_lshlrev_b32_e32 v128, 16, v56
	v_and_b32_e32 v129, 0xffff0000, v56
	v_lshlrev_b32_e32 v130, 16, v57
	v_and_b32_e32 v131, 0xffff0000, v57
	v_lshlrev_b32_e32 v132, 16, v58
	v_and_b32_e32 v133, 0xffff0000, v58
	v_lshlrev_b32_e32 v134, 16, v59
	v_and_b32_e32 v135, 0xffff0000, v59
	v_pk_mul_f32 v[136:137], v[60:61], v[128:129]
	v_pk_mul_f32 v[138:139], v[62:63], v[130:131]
	v_pk_mul_f32 v[140:141], v[64:65], v[132:133]
	v_pk_mul_f32 v[142:143], v[66:67], v[134:135]
	v_add_f32_e32 v36, v36, v136
	v_add_f32_e32 v36, v36, v137
	v_add_f32_e32 v36, v36, v138
	v_add_f32_e32 v36, v36, v139
	v_add_f32_e32 v36, v36, v140
	v_add_f32_e32 v36, v36, v141
	v_add_f32_e32 v36, v36, v142
	v_add_f32_e32 v36, v36, v143
	s_cmp_lt_i32 s3, 2
	s_cbranch_scc1 .Lmy_gd_c2
	v_pk_mul_f32 v[136:137], v[68:69], v[128:129]
	v_pk_mul_f32 v[138:139], v[70:71], v[130:131]
	v_pk_mul_f32 v[140:141], v[72:73], v[132:133]
	v_pk_mul_f32 v[142:143], v[74:75], v[134:135]
	v_add_f32_e32 v37, v37, v136
	v_add_f32_e32 v37, v37, v137
	v_add_f32_e32 v37, v37, v138
	v_add_f32_e32 v37, v37, v139
	v_add_f32_e32 v37, v37, v140
	v_add_f32_e32 v37, v37, v141
	v_add_f32_e32 v37, v37, v142
	v_add_f32_e32 v37, v37, v143
	s_cmp_lt_i32 s3, 3
	s_cbranch_scc1 .Lmy_gd_c2
	v_pk_mul_f32 v[136:137], v[76:77], v[128:129]
	v_pk_mul_f32 v[138:139], v[78:79], v[130:131]
	v_pk_mul_f32 v[140:141], v[80:81], v[132:133]
	v_pk_mul_f32 v[142:143], v[82:83], v[134:135]
	v_add_f32_e32 v38, v38, v136
	v_add_f32_e32 v38, v38, v137
	v_add_f32_e32 v38, v38, v138
	v_add_f32_e32 v38, v38, v139
	v_add_f32_e32 v38, v38, v140
	v_add_f32_e32 v38, v38, v141
	v_add_f32_e32 v38, v38, v142
	v_add_f32_e32 v38, v38, v143
	s_cmp_lt_i32 s3, 4
	s_cbranch_scc1 .Lmy_gd_c2
	v_pk_mul_f32 v[136:137], v[84:85], v[128:129]
	v_pk_mul_f32 v[138:139], v[86:87], v[130:131]
	v_pk_mul_f32 v[140:141], v[88:89], v[132:133]
	v_pk_mul_f32 v[142:143], v[90:91], v[134:135]
	v_add_f32_e32 v39, v39, v136
	v_add_f32_e32 v39, v39, v137
	v_add_f32_e32 v39, v39, v138
	v_add_f32_e32 v39, v39, v139
	v_add_f32_e32 v39, v39, v140
	v_add_f32_e32 v39, v39, v141
	v_add_f32_e32 v39, v39, v142
	v_add_f32_e32 v39, v39, v143
.Lmy_gd_c2:
	ds_read_b128 v[56:59], v32 offset:64
	ds_read_b128 v[60:63], v33 offset:128
	ds_read_b128 v[64:67], v33 offset:144
	ds_read_b128 v[68:71], v33 offset:2176
	ds_read_b128 v[72:75], v33 offset:2192
	ds_read_b128 v[76:79], v33 offset:4224
	ds_read_b128 v[80:83], v33 offset:4240
	ds_read_b128 v[84:87], v33 offset:6272
	ds_read_b128 v[88:91], v33 offset:6288
	s_waitcnt lgkmcnt(9)
	v_lshlrev_b32_e32 v128, 16, v92
	v_and_b32_e32 v129, 0xffff0000, v92
	v_lshlrev_b32_e32 v130, 16, v93
	v_and_b32_e32 v131, 0xffff0000, v93
	v_lshlrev_b32_e32 v132, 16, v94
	v_and_b32_e32 v133, 0xffff0000, v94
	v_lshlrev_b32_e32 v134, 16, v95
	v_and_b32_e32 v135, 0xffff0000, v95
	v_pk_mul_f32 v[136:137], v[96:97], v[128:129]
	v_pk_mul_f32 v[138:139], v[98:99], v[130:131]
	v_pk_mul_f32 v[140:141], v[100:101], v[132:133]
	v_pk_mul_f32 v[142:143], v[102:103], v[134:135]
	v_add_f32_e32 v36, v36, v136
	v_add_f32_e32 v36, v36, v137
	v_add_f32_e32 v36, v36, v138
	v_add_f32_e32 v36, v36, v139
	v_add_f32_e32 v36, v36, v140
	v_add_f32_e32 v36, v36, v141
	v_add_f32_e32 v36, v36, v142
	v_add_f32_e32 v36, v36, v143
	s_cmp_lt_i32 s3, 2
	s_cbranch_scc1 .Lmy_gd_c3
	v_pk_mul_f32 v[136:137], v[104:105], v[128:129]
	v_pk_mul_f32 v[138:139], v[106:107], v[130:131]
	v_pk_mul_f32 v[140:141], v[108:109], v[132:133]
	v_pk_mul_f32 v[142:143], v[110:111], v[134:135]
	v_add_f32_e32 v37, v37, v136
	v_add_f32_e32 v37, v37, v137
	v_add_f32_e32 v37, v37, v138
	v_add_f32_e32 v37, v37, v139
	v_add_f32_e32 v37, v37, v140
	v_add_f32_e32 v37, v37, v141
	v_add_f32_e32 v37, v37, v142
	v_add_f32_e32 v37, v37, v143
	s_cmp_lt_i32 s3, 3
	s_cbranch_scc1 .Lmy_gd_c3
	v_pk_mul_f32 v[136:137], v[112:113], v[128:129]
	v_pk_mul_f32 v[138:139], v[114:115], v[130:131]
	v_pk_mul_f32 v[140:141], v[116:117], v[132:133]
	v_pk_mul_f32 v[142:143], v[118:119], v[134:135]
	v_add_f32_e32 v38, v38, v136
	v_add_f32_e32 v38, v38, v137
	v_add_f32_e32 v38, v38, v138
	v_add_f32_e32 v38, v38, v139
	v_add_f32_e32 v38, v38, v140
	v_add_f32_e32 v38, v38, v141
	v_add_f32_e32 v38, v38, v142
	v_add_f32_e32 v38, v38, v143
	s_cmp_lt_i32 s3, 4
	s_cbranch_scc1 .Lmy_gd_c3
	v_pk_mul_f32 v[136:137], v[120:121], v[128:129]
	v_pk_mul_f32 v[138:139], v[122:123], v[130:131]
	v_pk_mul_f32 v[140:141], v[124:125], v[132:133]
	v_pk_mul_f32 v[142:143], v[126:127], v[134:135]
	v_add_f32_e32 v39, v39, v136
	v_add_f32_e32 v39, v39, v137
	v_add_f32_e32 v39, v39, v138
	v_add_f32_e32 v39, v39, v139
	v_add_f32_e32 v39, v39, v140
	v_add_f32_e32 v39, v39, v141
	v_add_f32_e32 v39, v39, v142
	v_add_f32_e32 v39, v39, v143
; DEVI float bfs(short h) { return __uint_as_float(((unsigned)(u16)h) << 16); }
; DEVI void moba_item(const Params& p, int l, int item) {
;     ...
; #pragma unroll
;     for (int c = 0; c < 16; ++c) {
;       const bf16x8 qv = *(const bf16x8*)(Qs + q * 136 + c * 8);
;       float qf[8];
; #pragma unroll
;       for (int e = 0; e < 8; ++e) qf[e] = bfs(qv[e]);
; #pragma unroll
;       for (int k = 0; k < 4; ++k) {
;         const int blk = part + 4 * k;
;         if (blk < qblk) {
; #pragma unroll
;           for (int e = 0; e < 8; ++e) dots[k] += qf[e] * km[blk * 128 + c * 8 + e];
;         }
;       }
;     }
.Lmy_gd_c3:
	ds_read_b128 v[92:95], v32 offset:80
	ds_read_b128 v[96:99], v33 offset:160
	ds_read_b128 v[100:103], v33 offset:176
	ds_read_b128 v[104:107], v33 offset:2208
	ds_read_b128 v[108:111], v33 offset:2224
	ds_read_b128 v[112:115], v33 offset:4256
	ds_read_b128 v[116:119], v33 offset:4272
	ds_read_b128 v[120:123], v33 offset:6304
	ds_read_b128 v[124:127], v33 offset:6320
	s_waitcnt lgkmcnt(9)
	v_lshlrev_b32_e32 v128, 16, v56
	v_and_b32_e32 v129, 0xffff0000, v56
	v_lshlrev_b32_e32 v130, 16, v57
	v_and_b32_e32 v131, 0xffff0000, v57
	v_lshlrev_b32_e32 v132, 16, v58
	v_and_b32_e32 v133, 0xffff0000, v58
	v_lshlrev_b32_e32 v134, 16, v59
	v_and_b32_e32 v135, 0xffff0000, v59
	v_pk_mul_f32 v[136:137], v[60:61], v[128:129]
	v_pk_mul_f32 v[138:139], v[62:63], v[130:131]
	v_pk_mul_f32 v[140:141], v[64:65], v[132:133]
	v_pk_mul_f32 v[142:143], v[66:67], v[134:135]
	v_add_f32_e32 v36, v36, v136
	v_add_f32_e32 v36, v36, v137
	v_add_f32_e32 v36, v36, v138
	v_add_f32_e32 v36, v36, v139
	v_add_f32_e32 v36, v36, v140
	v_add_f32_e32 v36, v36, v141
	v_add_f32_e32 v36, v36, v142
	v_add_f32_e32 v36, v36, v143
	s_cmp_lt_i32 s3, 2
	s_cbranch_scc1 .Lmy_gd_c4
	v_pk_mul_f32 v[136:137], v[68:69], v[128:129]
	v_pk_mul_f32 v[138:139], v[70:71], v[130:131]
	v_pk_mul_f32 v[140:141], v[72:73], v[132:133]
	v_pk_mul_f32 v[142:143], v[74:75], v[134:135]
	v_add_f32_e32 v37, v37, v136
	v_add_f32_e32 v37, v37, v137
	v_add_f32_e32 v37, v37, v138
	v_add_f32_e32 v37, v37, v139
	v_add_f32_e32 v37, v37, v140
	v_add_f32_e32 v37, v37, v141
	v_add_f32_e32 v37, v37, v142
	v_add_f32_e32 v37, v37, v143
	s_cmp_lt_i32 s3, 3
	s_cbranch_scc1 .Lmy_gd_c4
	v_pk_mul_f32 v[136:137], v[76:77], v[128:129]
	v_pk_mul_f32 v[138:139], v[78:79], v[130:131]
	v_pk_mul_f32 v[140:141], v[80:81], v[132:133]
	v_pk_mul_f32 v[142:143], v[82:83], v[134:135]
	v_add_f32_e32 v38, v38, v136
	v_add_f32_e32 v38, v38, v137
	v_add_f32_e32 v38, v38, v138
	v_add_f32_e32 v38, v38, v139
	v_add_f32_e32 v38, v38, v140
	v_add_f32_e32 v38, v38, v141
	v_add_f32_e32 v38, v38, v142
	v_add_f32_e32 v38, v38, v143
	s_cmp_lt_i32 s3, 4
	s_cbranch_scc1 .Lmy_gd_c4
	v_pk_mul_f32 v[136:137], v[84:85], v[128:129]
	v_pk_mul_f32 v[138:139], v[86:87], v[130:131]
	v_pk_mul_f32 v[140:141], v[88:89], v[132:133]
	v_pk_mul_f32 v[142:143], v[90:91], v[134:135]
	v_add_f32_e32 v39, v39, v136
	v_add_f32_e32 v39, v39, v137
	v_add_f32_e32 v39, v39, v138
	v_add_f32_e32 v39, v39, v139
	v_add_f32_e32 v39, v39, v140
	v_add_f32_e32 v39, v39, v141
	v_add_f32_e32 v39, v39, v142
	v_add_f32_e32 v39, v39, v143
.Lmy_gd_c4:
	ds_read_b128 v[56:59], v32 offset:96
	ds_read_b128 v[60:63], v33 offset:192
	ds_read_b128 v[64:67], v33 offset:208
	ds_read_b128 v[68:71], v33 offset:2240
	ds_read_b128 v[72:75], v33 offset:2256
	ds_read_b128 v[76:79], v33 offset:4288
	ds_read_b128 v[80:83], v33 offset:4304
	ds_read_b128 v[84:87], v33 offset:6336
	ds_read_b128 v[88:91], v33 offset:6352
	s_waitcnt lgkmcnt(9)
	v_lshlrev_b32_e32 v128, 16, v92
	v_and_b32_e32 v129, 0xffff0000, v92
	v_lshlrev_b32_e32 v130, 16, v93
	v_and_b32_e32 v131, 0xffff0000, v93
	v_lshlrev_b32_e32 v132, 16, v94
	v_and_b32_e32 v133, 0xffff0000, v94
	v_lshlrev_b32_e32 v134, 16, v95
	v_and_b32_e32 v135, 0xffff0000, v95
	v_pk_mul_f32 v[136:137], v[96:97], v[128:129]
	v_pk_mul_f32 v[138:139], v[98:99], v[130:131]
	v_pk_mul_f32 v[140:141], v[100:101], v[132:133]
	v_pk_mul_f32 v[142:143], v[102:103], v[134:135]
	v_add_f32_e32 v36, v36, v136
	v_add_f32_e32 v36, v36, v137
	v_add_f32_e32 v36, v36, v138
	v_add_f32_e32 v36, v36, v139
	v_add_f32_e32 v36, v36, v140
	v_add_f32_e32 v36, v36, v141
	v_add_f32_e32 v36, v36, v142
	v_add_f32_e32 v36, v36, v143
	s_cmp_lt_i32 s3, 2
	s_cbranch_scc1 .Lmy_gd_c5
	v_pk_mul_f32 v[136:137], v[104:105], v[128:129]
	v_pk_mul_f32 v[138:139], v[106:107], v[130:131]
	v_pk_mul_f32 v[140:141], v[108:109], v[132:133]
	v_pk_mul_f32 v[142:143], v[110:111], v[134:135]
	v_add_f32_e32 v37, v37, v136
	v_add_f32_e32 v37, v37, v137
	v_add_f32_e32 v37, v37, v138
	v_add_f32_e32 v37, v37, v139
	v_add_f32_e32 v37, v37, v140
	v_add_f32_e32 v37, v37, v141
	v_add_f32_e32 v37, v37, v142
	v_add_f32_e32 v37, v37, v143
	s_cmp_lt_i32 s3, 3
	s_cbranch_scc1 .Lmy_gd_c5
	v_pk_mul_f32 v[136:137], v[112:113], v[128:129]
	v_pk_mul_f32 v[138:139], v[114:115], v[130:131]
	v_pk_mul_f32 v[140:141], v[116:117], v[132:133]
	v_pk_mul_f32 v[142:143], v[118:119], v[134:135]
	v_add_f32_e32 v38, v38, v136
	v_add_f32_e32 v38, v38, v137
	v_add_f32_e32 v38, v38, v138
	v_add_f32_e32 v38, v38, v139
	v_add_f32_e32 v38, v38, v140
	v_add_f32_e32 v38, v38, v141
	v_add_f32_e32 v38, v38, v142
	v_add_f32_e32 v38, v38, v143
	s_cmp_lt_i32 s3, 4
	s_cbranch_scc1 .Lmy_gd_c5
	v_pk_mul_f32 v[136:137], v[120:121], v[128:129]
	v_pk_mul_f32 v[138:139], v[122:123], v[130:131]
	v_pk_mul_f32 v[140:141], v[124:125], v[132:133]
	v_pk_mul_f32 v[142:143], v[126:127], v[134:135]
	v_add_f32_e32 v39, v39, v136
	v_add_f32_e32 v39, v39, v137
	v_add_f32_e32 v39, v39, v138
	v_add_f32_e32 v39, v39, v139
	v_add_f32_e32 v39, v39, v140
	v_add_f32_e32 v39, v39, v141
	v_add_f32_e32 v39, v39, v142
	v_add_f32_e32 v39, v39, v143
; DEVI float bfs(short h) { return __uint_as_float(((unsigned)(u16)h) << 16); }
; DEVI void moba_item(const Params& p, int l, int item) {
;     ...
; #pragma unroll
;     for (int c = 0; c < 16; ++c) {
;       const bf16x8 qv = *(const bf16x8*)(Qs + q * 136 + c * 8);
;       float qf[8];
; #pragma unroll
;       for (int e = 0; e < 8; ++e) qf[e] = bfs(qv[e]);
; #pragma unroll
;       for (int k = 0; k < 4; ++k) {
;         const int blk = part + 4 * k;
;         if (blk < qblk) {
; #pragma unroll
;           for (int e = 0; e < 8; ++e) dots[k] += qf[e] * km[blk * 128 + c * 8 + e];
;         }
;       }
;     }
.Lmy_gd_c5:
	ds_read_b128 v[92:95], v32 offset:112
	ds_read_b128 v[96:99], v33 offset:224
	ds_read_b128 v[100:103], v33 offset:240
	ds_read_b128 v[104:107], v33 offset:2272
	ds_read_b128 v[108:111], v33 offset:2288
	ds_read_b128 v[112:115], v33 offset:4320
	ds_read_b128 v[116:119], v33 offset:4336
	ds_read_b128 v[120:123], v33 offset:6368
	ds_read_b128 v[124:127], v33 offset:6384
	s_waitcnt lgkmcnt(9)
	v_lshlrev_b32_e32 v128, 16, v56
	v_and_b32_e32 v129, 0xffff0000, v56
	v_lshlrev_b32_e32 v130, 16, v57
	v_and_b32_e32 v131, 0xffff0000, v57
	v_lshlrev_b32_e32 v132, 16, v58
	v_and_b32_e32 v133, 0xffff0000, v58
	v_lshlrev_b32_e32 v134, 16, v59
	v_and_b32_e32 v135, 0xffff0000, v59
	v_pk_mul_f32 v[136:137], v[60:61], v[128:129]
	v_pk_mul_f32 v[138:139], v[62:63], v[130:131]
	v_pk_mul_f32 v[140:141], v[64:65], v[132:133]
	v_pk_mul_f32 v[142:143], v[66:67], v[134:135]
	v_add_f32_e32 v36, v36, v136
	v_add_f32_e32 v36, v36, v137
	v_add_f32_e32 v36, v36, v138
	v_add_f32_e32 v36, v36, v139
	v_add_f32_e32 v36, v36, v140
	v_add_f32_e32 v36, v36, v141
	v_add_f32_e32 v36, v36, v142
	v_add_f32_e32 v36, v36, v143
	s_cmp_lt_i32 s3, 2
	s_cbranch_scc1 .Lmy_gd_c6
	v_pk_mul_f32 v[136:137], v[68:69], v[128:129]
	v_pk_mul_f32 v[138:139], v[70:71], v[130:131]
	v_pk_mul_f32 v[140:141], v[72:73], v[132:133]
	v_pk_mul_f32 v[142:143], v[74:75], v[134:135]
	v_add_f32_e32 v37, v37, v136
	v_add_f32_e32 v37, v37, v137
	v_add_f32_e32 v37, v37, v138
	v_add_f32_e32 v37, v37, v139
	v_add_f32_e32 v37, v37, v140
	v_add_f32_e32 v37, v37, v141
	v_add_f32_e32 v37, v37, v142
	v_add_f32_e32 v37, v37, v143
	s_cmp_lt_i32 s3, 3
	s_cbranch_scc1 .Lmy_gd_c6
	v_pk_mul_f32 v[136:137], v[76:77], v[128:129]
	v_pk_mul_f32 v[138:139], v[78:79], v[130:131]
	v_pk_mul_f32 v[140:141], v[80:81], v[132:133]
	v_pk_mul_f32 v[142:143], v[82:83], v[134:135]
	v_add_f32_e32 v38, v38, v136
	v_add_f32_e32 v38, v38, v137
	v_add_f32_e32 v38, v38, v138
	v_add_f32_e32 v38, v38, v139
	v_add_f32_e32 v38, v38, v140
	v_add_f32_e32 v38, v38, v141
	v_add_f32_e32 v38, v38, v142
	v_add_f32_e32 v38, v38, v143
	s_cmp_lt_i32 s3, 4
	s_cbranch_scc1 .Lmy_gd_c6
	v_pk_mul_f32 v[136:137], v[84:85], v[128:129]
	v_pk_mul_f32 v[138:139], v[86:87], v[130:131]
	v_pk_mul_f32 v[140:141], v[88:89], v[132:133]
	v_pk_mul_f32 v[142:143], v[90:91], v[134:135]
	v_add_f32_e32 v39, v39, v136
	v_add_f32_e32 v39, v39, v137
	v_add_f32_e32 v39, v39, v138
	v_add_f32_e32 v39, v39, v139
	v_add_f32_e32 v39, v39, v140
	v_add_f32_e32 v39, v39, v141
	v_add_f32_e32 v39, v39, v142
	v_add_f32_e32 v39, v39, v143
.Lmy_gd_c6:
	ds_read_b128 v[56:59], v32 offset:128
	ds_read_b128 v[60:63], v33 offset:256
	ds_read_b128 v[64:67], v33 offset:272
	ds_read_b128 v[68:71], v33 offset:2304
	ds_read_b128 v[72:75], v33 offset:2320
	ds_read_b128 v[76:79], v33 offset:4352
	ds_read_b128 v[80:83], v33 offset:4368
	ds_read_b128 v[84:87], v33 offset:6400
	ds_read_b128 v[88:91], v33 offset:6416
	s_waitcnt lgkmcnt(9)
	v_lshlrev_b32_e32 v128, 16, v92
	v_and_b32_e32 v129, 0xffff0000, v92
	v_lshlrev_b32_e32 v130, 16, v93
	v_and_b32_e32 v131, 0xffff0000, v93
	v_lshlrev_b32_e32 v132, 16, v94
	v_and_b32_e32 v133, 0xffff0000, v94
	v_lshlrev_b32_e32 v134, 16, v95
	v_and_b32_e32 v135, 0xffff0000, v95
	v_pk_mul_f32 v[136:137], v[96:97], v[128:129]
	v_pk_mul_f32 v[138:139], v[98:99], v[130:131]
	v_pk_mul_f32 v[140:141], v[100:101], v[132:133]
	v_pk_mul_f32 v[142:143], v[102:103], v[134:135]
	v_add_f32_e32 v36, v36, v136
	v_add_f32_e32 v36, v36, v137
	v_add_f32_e32 v36, v36, v138
	v_add_f32_e32 v36, v36, v139
	v_add_f32_e32 v36, v36, v140
	v_add_f32_e32 v36, v36, v141
	v_add_f32_e32 v36, v36, v142
	v_add_f32_e32 v36, v36, v143
	s_cmp_lt_i32 s3, 2
	s_cbranch_scc1 .Lmy_gd_c7
	v_pk_mul_f32 v[136:137], v[104:105], v[128:129]
	v_pk_mul_f32 v[138:139], v[106:107], v[130:131]
	v_pk_mul_f32 v[140:141], v[108:109], v[132:133]
	v_pk_mul_f32 v[142:143], v[110:111], v[134:135]
	v_add_f32_e32 v37, v37, v136
	v_add_f32_e32 v37, v37, v137
	v_add_f32_e32 v37, v37, v138
	v_add_f32_e32 v37, v37, v139
	v_add_f32_e32 v37, v37, v140
	v_add_f32_e32 v37, v37, v141
	v_add_f32_e32 v37, v37, v142
	v_add_f32_e32 v37, v37, v143
	s_cmp_lt_i32 s3, 3
	s_cbranch_scc1 .Lmy_gd_c7
	v_pk_mul_f32 v[136:137], v[112:113], v[128:129]
	v_pk_mul_f32 v[138:139], v[114:115], v[130:131]
	v_pk_mul_f32 v[140:141], v[116:117], v[132:133]
	v_pk_mul_f32 v[142:143], v[118:119], v[134:135]
	v_add_f32_e32 v38, v38, v136
	v_add_f32_e32 v38, v38, v137
	v_add_f32_e32 v38, v38, v138
	v_add_f32_e32 v38, v38, v139
	v_add_f32_e32 v38, v38, v140
	v_add_f32_e32 v38, v38, v141
	v_add_f32_e32 v38, v38, v142
	v_add_f32_e32 v38, v38, v143
	s_cmp_lt_i32 s3, 4
	s_cbranch_scc1 .Lmy_gd_c7
	v_pk_mul_f32 v[136:137], v[120:121], v[128:129]
	v_pk_mul_f32 v[138:139], v[122:123], v[130:131]
	v_pk_mul_f32 v[140:141], v[124:125], v[132:133]
	v_pk_mul_f32 v[142:143], v[126:127], v[134:135]
	v_add_f32_e32 v39, v39, v136
	v_add_f32_e32 v39, v39, v137
	v_add_f32_e32 v39, v39, v138
	v_add_f32_e32 v39, v39, v139
	v_add_f32_e32 v39, v39, v140
	v_add_f32_e32 v39, v39, v141
	v_add_f32_e32 v39, v39, v142
	v_add_f32_e32 v39, v39, v143
; DEVI float bfs(short h) { return __uint_as_float(((unsigned)(u16)h) << 16); }
; DEVI void moba_item(const Params& p, int l, int item) {
;     ...
; #pragma unroll
;     for (int c = 0; c < 16; ++c) {
;       const bf16x8 qv = *(const bf16x8*)(Qs + q * 136 + c * 8);
;       float qf[8];
; #pragma unroll
;       for (int e = 0; e < 8; ++e) qf[e] = bfs(qv[e]);
; #pragma unroll
;       for (int k = 0; k < 4; ++k) {
;         const int blk = part + 4 * k;
;         if (blk < qblk) {
; #pragma unroll
;           for (int e = 0; e < 8; ++e) dots[k] += qf[e] * km[blk * 128 + c * 8 + e];
;         }
;       }
;     }
.Lmy_gd_c7:
	ds_read_b128 v[92:95], v32 offset:144
	ds_read_b128 v[96:99], v33 offset:288
	ds_read_b128 v[100:103], v33 offset:304
	ds_read_b128 v[104:107], v33 offset:2336
	ds_read_b128 v[108:111], v33 offset:2352
	ds_read_b128 v[112:115], v33 offset:4384
	ds_read_b128 v[116:119], v33 offset:4400
	ds_read_b128 v[120:123], v33 offset:6432
	ds_read_b128 v[124:127], v33 offset:6448
	s_waitcnt lgkmcnt(9)
	v_lshlrev_b32_e32 v128, 16, v56
	v_and_b32_e32 v129, 0xffff0000, v56
	v_lshlrev_b32_e32 v130, 16, v57
	v_and_b32_e32 v131, 0xffff0000, v57
	v_lshlrev_b32_e32 v132, 16, v58
	v_and_b32_e32 v133, 0xffff0000, v58
	v_lshlrev_b32_e32 v134, 16, v59
	v_and_b32_e32 v135, 0xffff0000, v59
	v_pk_mul_f32 v[136:137], v[60:61], v[128:129]
	v_pk_mul_f32 v[138:139], v[62:63], v[130:131]
	v_pk_mul_f32 v[140:141], v[64:65], v[132:133]
	v_pk_mul_f32 v[142:143], v[66:67], v[134:135]
	v_add_f32_e32 v36, v36, v136
	v_add_f32_e32 v36, v36, v137
	v_add_f32_e32 v36, v36, v138
	v_add_f32_e32 v36, v36, v139
	v_add_f32_e32 v36, v36, v140
	v_add_f32_e32 v36, v36, v141
	v_add_f32_e32 v36, v36, v142
	v_add_f32_e32 v36, v36, v143
	s_cmp_lt_i32 s3, 2
	s_cbranch_scc1 .Lmy_gd_c8
	v_pk_mul_f32 v[136:137], v[68:69], v[128:129]
	v_pk_mul_f32 v[138:139], v[70:71], v[130:131]
	v_pk_mul_f32 v[140:141], v[72:73], v[132:133]
	v_pk_mul_f32 v[142:143], v[74:75], v[134:135]
	v_add_f32_e32 v37, v37, v136
	v_add_f32_e32 v37, v37, v137
	v_add_f32_e32 v37, v37, v138
	v_add_f32_e32 v37, v37, v139
	v_add_f32_e32 v37, v37, v140
	v_add_f32_e32 v37, v37, v141
	v_add_f32_e32 v37, v37, v142
	v_add_f32_e32 v37, v37, v143
	s_cmp_lt_i32 s3, 3
	s_cbranch_scc1 .Lmy_gd_c8
	v_pk_mul_f32 v[136:137], v[76:77], v[128:129]
	v_pk_mul_f32 v[138:139], v[78:79], v[130:131]
	v_pk_mul_f32 v[140:141], v[80:81], v[132:133]
	v_pk_mul_f32 v[142:143], v[82:83], v[134:135]
	v_add_f32_e32 v38, v38, v136
	v_add_f32_e32 v38, v38, v137
	v_add_f32_e32 v38, v38, v138
	v_add_f32_e32 v38, v38, v139
	v_add_f32_e32 v38, v38, v140
	v_add_f32_e32 v38, v38, v141
	v_add_f32_e32 v38, v38, v142
	v_add_f32_e32 v38, v38, v143
	s_cmp_lt_i32 s3, 4
	s_cbranch_scc1 .Lmy_gd_c8
	v_pk_mul_f32 v[136:137], v[84:85], v[128:129]
	v_pk_mul_f32 v[138:139], v[86:87], v[130:131]
	v_pk_mul_f32 v[140:141], v[88:89], v[132:133]
	v_pk_mul_f32 v[142:143], v[90:91], v[134:135]
	v_add_f32_e32 v39, v39, v136
	v_add_f32_e32 v39, v39, v137
	v_add_f32_e32 v39, v39, v138
	v_add_f32_e32 v39, v39, v139
	v_add_f32_e32 v39, v39, v140
	v_add_f32_e32 v39, v39, v141
	v_add_f32_e32 v39, v39, v142
	v_add_f32_e32 v39, v39, v143
.Lmy_gd_c8:
	ds_read_b128 v[56:59], v32 offset:160
	ds_read_b128 v[60:63], v33 offset:320
	ds_read_b128 v[64:67], v33 offset:336
	ds_read_b128 v[68:71], v33 offset:2368
	ds_read_b128 v[72:75], v33 offset:2384
	ds_read_b128 v[76:79], v33 offset:4416
	ds_read_b128 v[80:83], v33 offset:4432
	ds_read_b128 v[84:87], v33 offset:6464
	ds_read_b128 v[88:91], v33 offset:6480
	s_waitcnt lgkmcnt(9)
	v_lshlrev_b32_e32 v128, 16, v92
	v_and_b32_e32 v129, 0xffff0000, v92
	v_lshlrev_b32_e32 v130, 16, v93
	v_and_b32_e32 v131, 0xffff0000, v93
	v_lshlrev_b32_e32 v132, 16, v94
	v_and_b32_e32 v133, 0xffff0000, v94
	v_lshlrev_b32_e32 v134, 16, v95
	v_and_b32_e32 v135, 0xffff0000, v95
	v_pk_mul_f32 v[136:137], v[96:97], v[128:129]
	v_pk_mul_f32 v[138:139], v[98:99], v[130:131]
	v_pk_mul_f32 v[140:141], v[100:101], v[132:133]
	v_pk_mul_f32 v[142:143], v[102:103], v[134:135]
	v_add_f32_e32 v36, v36, v136
	v_add_f32_e32 v36, v36, v137
	v_add_f32_e32 v36, v36, v138
	v_add_f32_e32 v36, v36, v139
	v_add_f32_e32 v36, v36, v140
	v_add_f32_e32 v36, v36, v141
	v_add_f32_e32 v36, v36, v142
	v_add_f32_e32 v36, v36, v143
	s_cmp_lt_i32 s3, 2
	s_cbranch_scc1 .Lmy_gd_c9
	v_pk_mul_f32 v[136:137], v[104:105], v[128:129]
	v_pk_mul_f32 v[138:139], v[106:107], v[130:131]
	v_pk_mul_f32 v[140:141], v[108:109], v[132:133]
	v_pk_mul_f32 v[142:143], v[110:111], v[134:135]
	v_add_f32_e32 v37, v37, v136
	v_add_f32_e32 v37, v37, v137
	v_add_f32_e32 v37, v37, v138
	v_add_f32_e32 v37, v37, v139
	v_add_f32_e32 v37, v37, v140
	v_add_f32_e32 v37, v37, v141
	v_add_f32_e32 v37, v37, v142
	v_add_f32_e32 v37, v37, v143
	s_cmp_lt_i32 s3, 3
	s_cbranch_scc1 .Lmy_gd_c9
	v_pk_mul_f32 v[136:137], v[112:113], v[128:129]
	v_pk_mul_f32 v[138:139], v[114:115], v[130:131]
	v_pk_mul_f32 v[140:141], v[116:117], v[132:133]
	v_pk_mul_f32 v[142:143], v[118:119], v[134:135]
	v_add_f32_e32 v38, v38, v136
	v_add_f32_e32 v38, v38, v137
	v_add_f32_e32 v38, v38, v138
	v_add_f32_e32 v38, v38, v139
	v_add_f32_e32 v38, v38, v140
	v_add_f32_e32 v38, v38, v141
	v_add_f32_e32 v38, v38, v142
	v_add_f32_e32 v38, v38, v143
	s_cmp_lt_i32 s3, 4
	s_cbranch_scc1 .Lmy_gd_c9
	v_pk_mul_f32 v[136:137], v[120:121], v[128:129]
	v_pk_mul_f32 v[138:139], v[122:123], v[130:131]
	v_pk_mul_f32 v[140:141], v[124:125], v[132:133]
	v_pk_mul_f32 v[142:143], v[126:127], v[134:135]
	v_add_f32_e32 v39, v39, v136
	v_add_f32_e32 v39, v39, v137
	v_add_f32_e32 v39, v39, v138
	v_add_f32_e32 v39, v39, v139
	v_add_f32_e32 v39, v39, v140
	v_add_f32_e32 v39, v39, v141
	v_add_f32_e32 v39, v39, v142
	v_add_f32_e32 v39, v39, v143
; DEVI float bfs(short h) { return __uint_as_float(((unsigned)(u16)h) << 16); }
; DEVI void moba_item(const Params& p, int l, int item) {
;     ...
; #pragma unroll
;     for (int c = 0; c < 16; ++c) {
;       const bf16x8 qv = *(const bf16x8*)(Qs + q * 136 + c * 8);
;       float qf[8];
; #pragma unroll
;       for (int e = 0; e < 8; ++e) qf[e] = bfs(qv[e]);
; #pragma unroll
;       for (int k = 0; k < 4; ++k) {
;         const int blk = part + 4 * k;
;         if (blk < qblk) {
; #pragma unroll
;           for (int e = 0; e < 8; ++e) dots[k] += qf[e] * km[blk * 128 + c * 8 + e];
;         }
;       }
;     }
.Lmy_gd_c9:
	ds_read_b128 v[92:95], v32 offset:176
	ds_read_b128 v[96:99], v33 offset:352
	ds_read_b128 v[100:103], v33 offset:368
	ds_read_b128 v[104:107], v33 offset:2400
	ds_read_b128 v[108:111], v33 offset:2416
	ds_read_b128 v[112:115], v33 offset:4448
	ds_read_b128 v[116:119], v33 offset:4464
	ds_read_b128 v[120:123], v33 offset:6496
	ds_read_b128 v[124:127], v33 offset:6512
	s_waitcnt lgkmcnt(9)
	v_lshlrev_b32_e32 v128, 16, v56
	v_and_b32_e32 v129, 0xffff0000, v56
	v_lshlrev_b32_e32 v130, 16, v57
	v_and_b32_e32 v131, 0xffff0000, v57
	v_lshlrev_b32_e32 v132, 16, v58
	v_and_b32_e32 v133, 0xffff0000, v58
	v_lshlrev_b32_e32 v134, 16, v59
	v_and_b32_e32 v135, 0xffff0000, v59
	v_pk_mul_f32 v[136:137], v[60:61], v[128:129]
	v_pk_mul_f32 v[138:139], v[62:63], v[130:131]
	v_pk_mul_f32 v[140:141], v[64:65], v[132:133]
	v_pk_mul_f32 v[142:143], v[66:67], v[134:135]
	v_add_f32_e32 v36, v36, v136
	v_add_f32_e32 v36, v36, v137
	v_add_f32_e32 v36, v36, v138
	v_add_f32_e32 v36, v36, v139
	v_add_f32_e32 v36, v36, v140
	v_add_f32_e32 v36, v36, v141
	v_add_f32_e32 v36, v36, v142
	v_add_f32_e32 v36, v36, v143
	s_cmp_lt_i32 s3, 2
	s_cbranch_scc1 .Lmy_gd_c10
	v_pk_mul_f32 v[136:137], v[68:69], v[128:129]
	v_pk_mul_f32 v[138:139], v[70:71], v[130:131]
	v_pk_mul_f32 v[140:141], v[72:73], v[132:133]
	v_pk_mul_f32 v[142:143], v[74:75], v[134:135]
	v_add_f32_e32 v37, v37, v136
	v_add_f32_e32 v37, v37, v137
	v_add_f32_e32 v37, v37, v138
	v_add_f32_e32 v37, v37, v139
	v_add_f32_e32 v37, v37, v140
	v_add_f32_e32 v37, v37, v141
	v_add_f32_e32 v37, v37, v142
	v_add_f32_e32 v37, v37, v143
	s_cmp_lt_i32 s3, 3
	s_cbranch_scc1 .Lmy_gd_c10
	v_pk_mul_f32 v[136:137], v[76:77], v[128:129]
	v_pk_mul_f32 v[138:139], v[78:79], v[130:131]
	v_pk_mul_f32 v[140:141], v[80:81], v[132:133]
	v_pk_mul_f32 v[142:143], v[82:83], v[134:135]
	v_add_f32_e32 v38, v38, v136
	v_add_f32_e32 v38, v38, v137
	v_add_f32_e32 v38, v38, v138
	v_add_f32_e32 v38, v38, v139
	v_add_f32_e32 v38, v38, v140
	v_add_f32_e32 v38, v38, v141
	v_add_f32_e32 v38, v38, v142
	v_add_f32_e32 v38, v38, v143
	s_cmp_lt_i32 s3, 4
	s_cbranch_scc1 .Lmy_gd_c10
	v_pk_mul_f32 v[136:137], v[84:85], v[128:129]
	v_pk_mul_f32 v[138:139], v[86:87], v[130:131]
	v_pk_mul_f32 v[140:141], v[88:89], v[132:133]
	v_pk_mul_f32 v[142:143], v[90:91], v[134:135]
	v_add_f32_e32 v39, v39, v136
	v_add_f32_e32 v39, v39, v137
	v_add_f32_e32 v39, v39, v138
	v_add_f32_e32 v39, v39, v139
	v_add_f32_e32 v39, v39, v140
	v_add_f32_e32 v39, v39, v141
	v_add_f32_e32 v39, v39, v142
	v_add_f32_e32 v39, v39, v143
.Lmy_gd_c10:
	ds_read_b128 v[56:59], v32 offset:192
	ds_read_b128 v[60:63], v33 offset:384
	ds_read_b128 v[64:67], v33 offset:400
	ds_read_b128 v[68:71], v33 offset:2432
	ds_read_b128 v[72:75], v33 offset:2448
	ds_read_b128 v[76:79], v33 offset:4480
	ds_read_b128 v[80:83], v33 offset:4496
	ds_read_b128 v[84:87], v33 offset:6528
	ds_read_b128 v[88:91], v33 offset:6544
	s_waitcnt lgkmcnt(9)
	v_lshlrev_b32_e32 v128, 16, v92
	v_and_b32_e32 v129, 0xffff0000, v92
	v_lshlrev_b32_e32 v130, 16, v93
	v_and_b32_e32 v131, 0xffff0000, v93
	v_lshlrev_b32_e32 v132, 16, v94
	v_and_b32_e32 v133, 0xffff0000, v94
	v_lshlrev_b32_e32 v134, 16, v95
	v_and_b32_e32 v135, 0xffff0000, v95
	v_pk_mul_f32 v[136:137], v[96:97], v[128:129]
	v_pk_mul_f32 v[138:139], v[98:99], v[130:131]
	v_pk_mul_f32 v[140:141], v[100:101], v[132:133]
	v_pk_mul_f32 v[142:143], v[102:103], v[134:135]
	v_add_f32_e32 v36, v36, v136
	v_add_f32_e32 v36, v36, v137
	v_add_f32_e32 v36, v36, v138
	v_add_f32_e32 v36, v36, v139
	v_add_f32_e32 v36, v36, v140
	v_add_f32_e32 v36, v36, v141
	v_add_f32_e32 v36, v36, v142
	v_add_f32_e32 v36, v36, v143
	s_cmp_lt_i32 s3, 2
	s_cbranch_scc1 .Lmy_gd_c11
	v_pk_mul_f32 v[136:137], v[104:105], v[128:129]
	v_pk_mul_f32 v[138:139], v[106:107], v[130:131]
	v_pk_mul_f32 v[140:141], v[108:109], v[132:133]
	v_pk_mul_f32 v[142:143], v[110:111], v[134:135]
	v_add_f32_e32 v37, v37, v136
	v_add_f32_e32 v37, v37, v137
	v_add_f32_e32 v37, v37, v138
	v_add_f32_e32 v37, v37, v139
	v_add_f32_e32 v37, v37, v140
	v_add_f32_e32 v37, v37, v141
	v_add_f32_e32 v37, v37, v142
	v_add_f32_e32 v37, v37, v143
	s_cmp_lt_i32 s3, 3
	s_cbranch_scc1 .Lmy_gd_c11
	v_pk_mul_f32 v[136:137], v[112:113], v[128:129]
	v_pk_mul_f32 v[138:139], v[114:115], v[130:131]
	v_pk_mul_f32 v[140:141], v[116:117], v[132:133]
	v_pk_mul_f32 v[142:143], v[118:119], v[134:135]
	v_add_f32_e32 v38, v38, v136
	v_add_f32_e32 v38, v38, v137
	v_add_f32_e32 v38, v38, v138
	v_add_f32_e32 v38, v38, v139
	v_add_f32_e32 v38, v38, v140
	v_add_f32_e32 v38, v38, v141
	v_add_f32_e32 v38, v38, v142
	v_add_f32_e32 v38, v38, v143
	s_cmp_lt_i32 s3, 4
	s_cbranch_scc1 .Lmy_gd_c11
	v_pk_mul_f32 v[136:137], v[120:121], v[128:129]
	v_pk_mul_f32 v[138:139], v[122:123], v[130:131]
	v_pk_mul_f32 v[140:141], v[124:125], v[132:133]
	v_pk_mul_f32 v[142:143], v[126:127], v[134:135]
	v_add_f32_e32 v39, v39, v136
	v_add_f32_e32 v39, v39, v137
	v_add_f32_e32 v39, v39, v138
	v_add_f32_e32 v39, v39, v139
	v_add_f32_e32 v39, v39, v140
	v_add_f32_e32 v39, v39, v141
	v_add_f32_e32 v39, v39, v142
	v_add_f32_e32 v39, v39, v143
; DEVI float bfs(short h) { return __uint_as_float(((unsigned)(u16)h) << 16); }
; DEVI void moba_item(const Params& p, int l, int item) {
;     ...
; #pragma unroll
;     for (int c = 0; c < 16; ++c) {
;       const bf16x8 qv = *(const bf16x8*)(Qs + q * 136 + c * 8);
;       float qf[8];
; #pragma unroll
;       for (int e = 0; e < 8; ++e) qf[e] = bfs(qv[e]);
; #pragma unroll
;       for (int k = 0; k < 4; ++k) {
;         const int blk = part + 4 * k;
;         if (blk < qblk) {
; #pragma unroll
;           for (int e = 0; e < 8; ++e) dots[k] += qf[e] * km[blk * 128 + c * 8 + e];
;         }
;       }
;     }
.Lmy_gd_c11:
	ds_read_b128 v[92:95], v32 offset:208
	ds_read_b128 v[96:99], v33 offset:416
	ds_read_b128 v[100:103], v33 offset:432
	ds_read_b128 v[104:107], v33 offset:2464
	ds_read_b128 v[108:111], v33 offset:2480
	ds_read_b128 v[112:115], v33 offset:4512
	ds_read_b128 v[116:119], v33 offset:4528
	ds_read_b128 v[120:123], v33 offset:6560
	ds_read_b128 v[124:127], v33 offset:6576
	s_waitcnt lgkmcnt(9)
	v_lshlrev_b32_e32 v128, 16, v56
	v_and_b32_e32 v129, 0xffff0000, v56
	v_lshlrev_b32_e32 v130, 16, v57
	v_and_b32_e32 v131, 0xffff0000, v57
	v_lshlrev_b32_e32 v132, 16, v58
	v_and_b32_e32 v133, 0xffff0000, v58
	v_lshlrev_b32_e32 v134, 16, v59
	v_and_b32_e32 v135, 0xffff0000, v59
	v_pk_mul_f32 v[136:137], v[60:61], v[128:129]
	v_pk_mul_f32 v[138:139], v[62:63], v[130:131]
	v_pk_mul_f32 v[140:141], v[64:65], v[132:133]
	v_pk_mul_f32 v[142:143], v[66:67], v[134:135]
	v_add_f32_e32 v36, v36, v136
	v_add_f32_e32 v36, v36, v137
	v_add_f32_e32 v36, v36, v138
	v_add_f32_e32 v36, v36, v139
	v_add_f32_e32 v36, v36, v140
	v_add_f32_e32 v36, v36, v141
	v_add_f32_e32 v36, v36, v142
	v_add_f32_e32 v36, v36, v143
	s_cmp_lt_i32 s3, 2
	s_cbranch_scc1 .Lmy_gd_c12
	v_pk_mul_f32 v[136:137], v[68:69], v[128:129]
	v_pk_mul_f32 v[138:139], v[70:71], v[130:131]
	v_pk_mul_f32 v[140:141], v[72:73], v[132:133]
	v_pk_mul_f32 v[142:143], v[74:75], v[134:135]
	v_add_f32_e32 v37, v37, v136
	v_add_f32_e32 v37, v37, v137
	v_add_f32_e32 v37, v37, v138
	v_add_f32_e32 v37, v37, v139
	v_add_f32_e32 v37, v37, v140
	v_add_f32_e32 v37, v37, v141
	v_add_f32_e32 v37, v37, v142
	v_add_f32_e32 v37, v37, v143
	s_cmp_lt_i32 s3, 3
	s_cbranch_scc1 .Lmy_gd_c12
	v_pk_mul_f32 v[136:137], v[76:77], v[128:129]
	v_pk_mul_f32 v[138:139], v[78:79], v[130:131]
	v_pk_mul_f32 v[140:141], v[80:81], v[132:133]
	v_pk_mul_f32 v[142:143], v[82:83], v[134:135]
	v_add_f32_e32 v38, v38, v136
	v_add_f32_e32 v38, v38, v137
	v_add_f32_e32 v38, v38, v138
	v_add_f32_e32 v38, v38, v139
	v_add_f32_e32 v38, v38, v140
	v_add_f32_e32 v38, v38, v141
	v_add_f32_e32 v38, v38, v142
	v_add_f32_e32 v38, v38, v143
	s_cmp_lt_i32 s3, 4
	s_cbranch_scc1 .Lmy_gd_c12
	v_pk_mul_f32 v[136:137], v[84:85], v[128:129]
	v_pk_mul_f32 v[138:139], v[86:87], v[130:131]
	v_pk_mul_f32 v[140:141], v[88:89], v[132:133]
	v_pk_mul_f32 v[142:143], v[90:91], v[134:135]
	v_add_f32_e32 v39, v39, v136
	v_add_f32_e32 v39, v39, v137
	v_add_f32_e32 v39, v39, v138
	v_add_f32_e32 v39, v39, v139
	v_add_f32_e32 v39, v39, v140
	v_add_f32_e32 v39, v39, v141
	v_add_f32_e32 v39, v39, v142
	v_add_f32_e32 v39, v39, v143
.Lmy_gd_c12:
	ds_read_b128 v[56:59], v32 offset:224
	ds_read_b128 v[60:63], v33 offset:448
	ds_read_b128 v[64:67], v33 offset:464
	ds_read_b128 v[68:71], v33 offset:2496
	ds_read_b128 v[72:75], v33 offset:2512
	ds_read_b128 v[76:79], v33 offset:4544
	ds_read_b128 v[80:83], v33 offset:4560
	ds_read_b128 v[84:87], v33 offset:6592
	ds_read_b128 v[88:91], v33 offset:6608
	s_waitcnt lgkmcnt(9)
	v_lshlrev_b32_e32 v128, 16, v92
	v_and_b32_e32 v129, 0xffff0000, v92
	v_lshlrev_b32_e32 v130, 16, v93
	v_and_b32_e32 v131, 0xffff0000, v93
	v_lshlrev_b32_e32 v132, 16, v94
	v_and_b32_e32 v133, 0xffff0000, v94
	v_lshlrev_b32_e32 v134, 16, v95
	v_and_b32_e32 v135, 0xffff0000, v95
	v_pk_mul_f32 v[136:137], v[96:97], v[128:129]
	v_pk_mul_f32 v[138:139], v[98:99], v[130:131]
	v_pk_mul_f32 v[140:141], v[100:101], v[132:133]
	v_pk_mul_f32 v[142:143], v[102:103], v[134:135]
	v_add_f32_e32 v36, v36, v136
	v_add_f32_e32 v36, v36, v137
	v_add_f32_e32 v36, v36, v138
	v_add_f32_e32 v36, v36, v139
	v_add_f32_e32 v36, v36, v140
	v_add_f32_e32 v36, v36, v141
	v_add_f32_e32 v36, v36, v142
	v_add_f32_e32 v36, v36, v143
	s_cmp_lt_i32 s3, 2
	s_cbranch_scc1 .Lmy_gd_c13
	v_pk_mul_f32 v[136:137], v[104:105], v[128:129]
	v_pk_mul_f32 v[138:139], v[106:107], v[130:131]
	v_pk_mul_f32 v[140:141], v[108:109], v[132:133]
	v_pk_mul_f32 v[142:143], v[110:111], v[134:135]
	v_add_f32_e32 v37, v37, v136
	v_add_f32_e32 v37, v37, v137
	v_add_f32_e32 v37, v37, v138
	v_add_f32_e32 v37, v37, v139
	v_add_f32_e32 v37, v37, v140
	v_add_f32_e32 v37, v37, v141
	v_add_f32_e32 v37, v37, v142
	v_add_f32_e32 v37, v37, v143
	s_cmp_lt_i32 s3, 3
	s_cbranch_scc1 .Lmy_gd_c13
	v_pk_mul_f32 v[136:137], v[112:113], v[128:129]
	v_pk_mul_f32 v[138:139], v[114:115], v[130:131]
	v_pk_mul_f32 v[140:141], v[116:117], v[132:133]
	v_pk_mul_f32 v[142:143], v[118:119], v[134:135]
	v_add_f32_e32 v38, v38, v136
	v_add_f32_e32 v38, v38, v137
	v_add_f32_e32 v38, v38, v138
	v_add_f32_e32 v38, v38, v139
	v_add_f32_e32 v38, v38, v140
	v_add_f32_e32 v38, v38, v141
	v_add_f32_e32 v38, v38, v142
	v_add_f32_e32 v38, v38, v143
	s_cmp_lt_i32 s3, 4
	s_cbranch_scc1 .Lmy_gd_c13
	v_pk_mul_f32 v[136:137], v[120:121], v[128:129]
	v_pk_mul_f32 v[138:139], v[122:123], v[130:131]
	v_pk_mul_f32 v[140:141], v[124:125], v[132:133]
	v_pk_mul_f32 v[142:143], v[126:127], v[134:135]
	v_add_f32_e32 v39, v39, v136
	v_add_f32_e32 v39, v39, v137
	v_add_f32_e32 v39, v39, v138
	v_add_f32_e32 v39, v39, v139
	v_add_f32_e32 v39, v39, v140
	v_add_f32_e32 v39, v39, v141
	v_add_f32_e32 v39, v39, v142
	v_add_f32_e32 v39, v39, v143
; DEVI float bfs(short h) { return __uint_as_float(((unsigned)(u16)h) << 16); }
; DEVI void moba_item(const Params& p, int l, int item) {
;     ...
; #pragma unroll
;     for (int c = 0; c < 16; ++c) {
;       const bf16x8 qv = *(const bf16x8*)(Qs + q * 136 + c * 8);
;       float qf[8];
; #pragma unroll
;       for (int e = 0; e < 8; ++e) qf[e] = bfs(qv[e]);
; #pragma unroll
;       for (int k = 0; k < 4; ++k) {
;         const int blk = part + 4 * k;
;         if (blk < qblk) {
; #pragma unroll
;           for (int e = 0; e < 8; ++e) dots[k] += qf[e] * km[blk * 128 + c * 8 + e];
;         }
;       }
;     }
; #pragma unroll
;     for (int k = 0; k < 4; ++k) {
;       const int blk = part + 4 * k;
;       if (blk < qblk) gate[q * 17 + blk] = dots[k];
;     }
;   }
;   __syncthreads();
;   if (tid < 128) {
;     float v1 = -INFINITY, v2 = -INFINITY, v3 = -INFINITY;
;     int i1 = -1, i2 = -1, i3 = -1;
;     for (int blk = 0; blk < qblk; ++blk) {
.Lmy_gd_c13:
	ds_read_b128 v[92:95], v32 offset:240
	ds_read_b128 v[96:99], v33 offset:480
	ds_read_b128 v[100:103], v33 offset:496
	ds_read_b128 v[104:107], v33 offset:2528
	ds_read_b128 v[108:111], v33 offset:2544
	ds_read_b128 v[112:115], v33 offset:4576
	ds_read_b128 v[116:119], v33 offset:4592
	ds_read_b128 v[120:123], v33 offset:6624
	ds_read_b128 v[124:127], v33 offset:6640
	s_waitcnt lgkmcnt(9)
	v_lshlrev_b32_e32 v128, 16, v56
	v_and_b32_e32 v129, 0xffff0000, v56
	v_lshlrev_b32_e32 v130, 16, v57
	v_and_b32_e32 v131, 0xffff0000, v57
	v_lshlrev_b32_e32 v132, 16, v58
	v_and_b32_e32 v133, 0xffff0000, v58
	v_lshlrev_b32_e32 v134, 16, v59
	v_and_b32_e32 v135, 0xffff0000, v59
	v_pk_mul_f32 v[136:137], v[60:61], v[128:129]
	v_pk_mul_f32 v[138:139], v[62:63], v[130:131]
	v_pk_mul_f32 v[140:141], v[64:65], v[132:133]
	v_pk_mul_f32 v[142:143], v[66:67], v[134:135]
	v_add_f32_e32 v36, v36, v136
	v_add_f32_e32 v36, v36, v137
	v_add_f32_e32 v36, v36, v138
	v_add_f32_e32 v36, v36, v139
	v_add_f32_e32 v36, v36, v140
	v_add_f32_e32 v36, v36, v141
	v_add_f32_e32 v36, v36, v142
	v_add_f32_e32 v36, v36, v143
	s_cmp_lt_i32 s3, 2
	s_cbranch_scc1 .Lmy_gd_c14
	v_pk_mul_f32 v[136:137], v[68:69], v[128:129]
	v_pk_mul_f32 v[138:139], v[70:71], v[130:131]
	v_pk_mul_f32 v[140:141], v[72:73], v[132:133]
	v_pk_mul_f32 v[142:143], v[74:75], v[134:135]
	v_add_f32_e32 v37, v37, v136
	v_add_f32_e32 v37, v37, v137
	v_add_f32_e32 v37, v37, v138
	v_add_f32_e32 v37, v37, v139
	v_add_f32_e32 v37, v37, v140
	v_add_f32_e32 v37, v37, v141
	v_add_f32_e32 v37, v37, v142
	v_add_f32_e32 v37, v37, v143
	s_cmp_lt_i32 s3, 3
	s_cbranch_scc1 .Lmy_gd_c14
	v_pk_mul_f32 v[136:137], v[76:77], v[128:129]
	v_pk_mul_f32 v[138:139], v[78:79], v[130:131]
	v_pk_mul_f32 v[140:141], v[80:81], v[132:133]
	v_pk_mul_f32 v[142:143], v[82:83], v[134:135]
	v_add_f32_e32 v38, v38, v136
	v_add_f32_e32 v38, v38, v137
	v_add_f32_e32 v38, v38, v138
	v_add_f32_e32 v38, v38, v139
	v_add_f32_e32 v38, v38, v140
	v_add_f32_e32 v38, v38, v141
	v_add_f32_e32 v38, v38, v142
	v_add_f32_e32 v38, v38, v143
	s_cmp_lt_i32 s3, 4
	s_cbranch_scc1 .Lmy_gd_c14
	v_pk_mul_f32 v[136:137], v[84:85], v[128:129]
	v_pk_mul_f32 v[138:139], v[86:87], v[130:131]
	v_pk_mul_f32 v[140:141], v[88:89], v[132:133]
	v_pk_mul_f32 v[142:143], v[90:91], v[134:135]
	v_add_f32_e32 v39, v39, v136
	v_add_f32_e32 v39, v39, v137
	v_add_f32_e32 v39, v39, v138
	v_add_f32_e32 v39, v39, v139
	v_add_f32_e32 v39, v39, v140
	v_add_f32_e32 v39, v39, v141
	v_add_f32_e32 v39, v39, v142
	v_add_f32_e32 v39, v39, v143
.Lmy_gd_c14:
	s_waitcnt lgkmcnt(0)
	v_lshlrev_b32_e32 v128, 16, v92
	v_and_b32_e32 v129, 0xffff0000, v92
	v_lshlrev_b32_e32 v130, 16, v93
	v_and_b32_e32 v131, 0xffff0000, v93
	v_lshlrev_b32_e32 v132, 16, v94
	v_and_b32_e32 v133, 0xffff0000, v94
	v_lshlrev_b32_e32 v134, 16, v95
	v_and_b32_e32 v135, 0xffff0000, v95
	v_pk_mul_f32 v[136:137], v[96:97], v[128:129]
	v_pk_mul_f32 v[138:139], v[98:99], v[130:131]
	v_pk_mul_f32 v[140:141], v[100:101], v[132:133]
	v_pk_mul_f32 v[142:143], v[102:103], v[134:135]
	v_add_f32_e32 v36, v36, v136
	v_add_f32_e32 v36, v36, v137
	v_add_f32_e32 v36, v36, v138
	v_add_f32_e32 v36, v36, v139
	v_add_f32_e32 v36, v36, v140
	v_add_f32_e32 v36, v36, v141
	v_add_f32_e32 v36, v36, v142
	v_add_f32_e32 v36, v36, v143
	s_cmp_lt_i32 s3, 2
	s_cbranch_scc1 .Lmy_gd_c15
	v_pk_mul_f32 v[136:137], v[104:105], v[128:129]
	v_pk_mul_f32 v[138:139], v[106:107], v[130:131]
	v_pk_mul_f32 v[140:141], v[108:109], v[132:133]
	v_pk_mul_f32 v[142:143], v[110:111], v[134:135]
	v_add_f32_e32 v37, v37, v136
	v_add_f32_e32 v37, v37, v137
	v_add_f32_e32 v37, v37, v138
	v_add_f32_e32 v37, v37, v139
	v_add_f32_e32 v37, v37, v140
	v_add_f32_e32 v37, v37, v141
	v_add_f32_e32 v37, v37, v142
	v_add_f32_e32 v37, v37, v143
	s_cmp_lt_i32 s3, 3
	s_cbranch_scc1 .Lmy_gd_c15
	v_pk_mul_f32 v[136:137], v[112:113], v[128:129]
	v_pk_mul_f32 v[138:139], v[114:115], v[130:131]
	v_pk_mul_f32 v[140:141], v[116:117], v[132:133]
	v_pk_mul_f32 v[142:143], v[118:119], v[134:135]
	v_add_f32_e32 v38, v38, v136
	v_add_f32_e32 v38, v38, v137
	v_add_f32_e32 v38, v38, v138
	v_add_f32_e32 v38, v38, v139
	v_add_f32_e32 v38, v38, v140
	v_add_f32_e32 v38, v38, v141
	v_add_f32_e32 v38, v38, v142
	v_add_f32_e32 v38, v38, v143
	s_cmp_lt_i32 s3, 4
	s_cbranch_scc1 .Lmy_gd_c15
	v_pk_mul_f32 v[136:137], v[120:121], v[128:129]
	v_pk_mul_f32 v[138:139], v[122:123], v[130:131]
	v_pk_mul_f32 v[140:141], v[124:125], v[132:133]
	v_pk_mul_f32 v[142:143], v[126:127], v[134:135]
	v_add_f32_e32 v39, v39, v136
	v_add_f32_e32 v39, v39, v137
	v_add_f32_e32 v39, v39, v138
	v_add_f32_e32 v39, v39, v139
	v_add_f32_e32 v39, v39, v140
	v_add_f32_e32 v39, v39, v141
	v_add_f32_e32 v39, v39, v142
	v_add_f32_e32 v39, v39, v143
.Lmy_gd_c15:
	v_mov_b32_e32 v34, s96
	v_mad_u32_u24 v34, v40, s74, v34
	v_lshl_add_u32 v34, v35, 2, v34
	ds_write_b32 v34, v36
	s_cmp_lt_i32 s3, 2
	s_cbranch_scc1 .Lmy_gd_done
	ds_write_b32 v34, v37 offset:16
	s_cmp_lt_i32 s3, 3
	s_cbranch_scc1 .Lmy_gd_done
	ds_write_b32 v34, v38 offset:32
	s_cmp_lt_i32 s3, 4
	s_cbranch_scc1 .Lmy_gd_done
	ds_write_b32 v34, v39 offset:48
.Lmy_gd_done:
	v_cmp_gt_u32_e32 vcc, s67, v48
	s_waitcnt lgkmcnt(0)
	s_barrier
	s_and_saveexec_b64 s[2:3], vcc
	s_cbranch_execz .LBB0_653
	v_mov_b32_e32 v41, -1
	s_cmp_lt_u32 s20, 2
	v_mov_b32_e32 v38, -1
	v_mov_b32_e32 v33, -1
	s_cbranch_scc1 .LBB0_649
	v_mov_b32_e32 v32, s96
	v_mad_u32_u24 v32, v48, s74, v32
	s_mov_b32 s21, 0
	v_mov_b32_e32 v37, -1
	v_mov_b32_e32 v34, 0xff800000
	v_mov_b32_e32 v35, 0xff800000
	v_mov_b32_e32 v39, 0xff800000
	v_mov_b32_e32 v36, -1
	v_mov_b32_e32 v33, -1

; DEVI void moba_item(const Params& p, int l, int item) {
;     ...
;     for (int blk = 0; blk < qblk; ++blk) {
;       float g = gate[tid * 17 + blk];
;       if (g > v1 || i1 < 0) { v3 = v2; i3 = i2; v2 = v1; i2 = i1; v1 = g; i1 = blk; }
;       else if (g > v2 || i2 < 0) { v3 = v2; i3 = i2; v2 = g; i2 = blk; }
;       else if (g > v3 || i3 < 0) { v3 = g; i3 = blk; }
;     }
;     unsigned mask = 0u;
;     if (i1 >= 0) mask |= 1u << i1;
;     if (i2 >= 0) mask |= 1u << i2;
;     if (i3 >= 0) mask |= 1u << i3;
;     selm[tid] = mask;
.LBB0_599:
	s_or_b64 exec, exec, s[8:9]
	s_add_i32 s21, s21, 1
	v_mov_b32_e32 v33, v36
	s_cmp_eq_u32 s28, s21
	v_add_u32_e32 v32, 4, v32
	s_cbranch_scc1 .LBB0_649
	v_mov_b32_e32 v39, v35
	v_mov_b32_e32 v34, v40
	v_mov_b32_e32 v35, v42
	v_mov_b32_e32 v37, v41
	v_mov_b32_e32 v36, v38
	s_branch .LBB0_595
.LBB0_649:
	v_lshlrev_b32_e64 v32, v41, 1
	v_cmp_lt_i32_e32 vcc, -1, v41
	v_lshlrev_b32_e64 v34, v38, 1
	v_lshlrev_b32_e64 v35, v33, 1
	v_cndmask_b32_e32 v32, 0, v32, vcc
	v_cmp_lt_i32_e32 vcc, -1, v38
	s_mov_b32 s8, 0
	s_mov_b64 s[6:7], exec
	v_cndmask_b32_e32 v34, 0, v34, vcc
	v_cmp_lt_i32_e32 vcc, -1, v33
	s_nop 1
	v_cndmask_b32_e32 v33, 0, v35, vcc
	v_or3_b32 v32, v34, v33, v32
	v_lshl_add_u32 v33, v48, 2, 0
	v_add_u32_e32 v33, 0x1e200, v33
	ds_write_b32 v33, v32

; DEVI void moba_item(const Params& p, int l, int item) {
;     ...
;   while (cblk >= 0) {
;     u16* Kc = par ? Kb1 : Kb0; u16* Vc = par ? Vb1 : Vb0;
;     u16* Kn = par ? Kb0 : Kb1; u16* Vn = par ? Vb0 : Vb1;
;     int n2blk = -1, n2half = 0;
;     if (nblk >= 0) {
; #pragma unroll
;       for (int i = 0; i < 4; ++i) {
;         *(bf16x8*)(Kn + (kkey + 32 * i) * 136 + kdg * 8) = pk_[i];
;         *(bf16x8*)(Vn + (kkey + 32 * i) * 144 + kdg * 8) = pv_[i];
;       }
;       MOBA_NEXT(nblk, nhalf, n2blk, n2half);
;       if (n2blk >= 0) MOBA_LOAD(n2blk, n2half);
.LBB0_656:
	s_cmp_eq_u32 s31, 0
	s_cselect_b64 s[2:3], -1, 0
	s_cmp_lt_i32 s34, 0
	s_cselect_b64 s[20:21], -1, 0
	s_mov_b32 s35, s34
	v_readfirstlane_b32 s6, v234
	s_cmpk_lt_u32 s6, 0x100
	s_cbranch_scc1 .LBB0_661
	s_and_b64 vcc, exec, s[20:21]
	s_cbranch_vccz .LBB0_658
	s_mov_b64 s[22:23], 0
	s_mov_b32 s34, -1
	s_branch .LBB0_661

; DEVI void moba_item(const Params& p, int l, int item) {
;     ...
;     if (nblk >= 0) {
; #pragma unroll
;       for (int i = 0; i < 4; ++i) {
;         *(bf16x8*)(Kn + (kkey + 32 * i) * 136 + kdg * 8) = pk_[i];
;         *(bf16x8*)(Vn + (kkey + 32 * i) * 144 + kdg * 8) = pv_[i];
;       }
;       MOBA_NEXT(nblk, nhalf, n2blk, n2half);
;       if (n2blk >= 0) MOBA_LOAD(n2blk, n2half);
;     }
;     const bool own = (cblk == qblk);
;     const bool lanesel = own ? true : (((mysel >> cblk) & 1u) != 0u);
;     if (own) {
;       if (chalf * 128 <= (qt & 1) * 128 + w * 16 + 15) moba_half<true>(Kc, Vc, chalf * 128, qb, oacc, m, lsum, true, qinb, lane);
;     } else if (__any(lanesel)) {
;       moba_half<false>(Kc, Vc, 0, qb, oacc, m, lsum, lanesel, qinb, lane);
;     }
;     __syncthreads();
;     cblk = nblk; chalf = nhalf; nblk = n2blk; nhalf = n2half; par ^= 1;
.Lmy_moba_endstage:
	v_readfirstlane_b32 s6, v234
	s_cmpk_lt_u32 s6, 0x100
	s_cbranch_scc0 .LBB0_669
	s_cmp_eq_u32 s31, 0
	s_cselect_b64 s[2:3], -1, 0
	s_and_b64 vcc, exec, s[20:21]
	s_cbranch_vccz .Lmy_moba_658
	s_mov_b64 s[22:23], 0
	s_mov_b32 s34, -1
	s_branch .LBB0_669
.Lmy_moba_658:
	s_and_b64 s[6:7], s[2:3], exec
	s_cselect_b32 s6, s72, s78
	s_cselect_b32 s7, s70, 0
	s_cmp_eq_u32 s35, s28
	v_add3_u32 v178, s7, v210, v155
	v_add3_u32 v179, s6, v210, v159
	s_cselect_b64 s[6:7], -1, 0
	s_and_b64 s[6:7], s[8:9], s[6:7]
	s_waitcnt vmcnt(7)
	ds_write_b128 v178, v[0:3]
	s_waitcnt vmcnt(6)
	ds_write_b128 v179, v[4:7]
	s_waitcnt vmcnt(5)
	ds_write_b128 v178, v[8:11] offset:8704
	s_waitcnt vmcnt(4)
	ds_write_b128 v179, v[12:15] offset:9216
	s_waitcnt vmcnt(3)
	ds_write_b128 v178, v[16:19] offset:17408
	s_waitcnt vmcnt(2)
	ds_write_b128 v179, v[20:23] offset:18432
	s_waitcnt vmcnt(1)
	ds_write_b128 v178, v[24:27] offset:26112
	s_waitcnt vmcnt(0)
	ds_write_b128 v179, v[28:31] offset:27648
	s_or_b64 s[6:7], s[10:11], s[6:7]
	v_sub_co_u32_e64 v178, s[22:23], s30, 1
	s_ff1_i32_b32 s34, s30
	s_and_b64 s[22:23], s[22:23], exec
	s_cselect_b32 s34, -1, s34
	s_and_b64 s[22:23], s[6:7], exec
	v_readfirstlane_b32 s22, v178
	s_cselect_b32 s23, s34, s35
	s_cselect_b32 s22, s22, -1
	s_cmp_lt_i32 s23, 0
	s_mov_b32 s34, -1
	s_cbranch_scc1 .Lmy_moba_660
	s_lshl_b32 s34, s23, 8
	s_add_i32 s34, s34, s29
	s_and_b64 s[36:37], s[6:7], exec
	s_cselect_b32 s36, 0, 0x80
	s_or_b32 s34, s34, s36
	v_or_b32_e32 v26, s34, v154
	v_mov_b64_e32 v[24:25], s[92:93]
	v_mad_u64_u32 v[0:1], s[36:37], v26, s97, v[24:25]
	v_lshl_add_u64 v[0:1], v[0:1], 0, s[98:99]
	v_or_b32_e32 v8, 32, v26
	v_lshl_add_u64 v[0:1], v[0:1], 0, v[210:211]
	v_mad_u64_u32 v[8:9], s[36:37], v8, s97, v[24:25]
	v_add_co_u32_e32 v4, vcc, s68, v0
	v_lshl_add_u64 v[8:9], v[8:9], 0, s[98:99]
	v_or_b32_e32 v16, 64, v26
	v_addc_co_u32_e32 v5, vcc, 0, v1, vcc
	v_lshl_add_u64 v[8:9], v[8:9], 0, v[210:211]
	v_mad_u64_u32 v[16:17], s[36:37], v16, s97, v[24:25]
	v_add_co_u32_e32 v12, vcc, s68, v8
	v_lshl_add_u64 v[16:17], v[16:17], 0, s[98:99]
	v_or_b32_e32 v26, 0x60, v26
	v_addc_co_u32_e32 v13, vcc, 0, v9, vcc
	v_lshl_add_u64 v[16:17], v[16:17], 0, v[210:211]
	v_mad_u64_u32 v[24:25], s[36:37], v26, s97, v[24:25]
	v_add_co_u32_e32 v20, vcc, s68, v16
	v_lshl_add_u64 v[24:25], v[24:25], 0, s[98:99]
	s_nop 0
	v_addc_co_u32_e32 v21, vcc, 0, v17, vcc
	v_lshl_add_u64 v[24:25], v[24:25], 0, v[210:211]
	v_add_co_u32_e32 v28, vcc, 0x3000, v24
	global_load_dwordx4 v[0:3], v[4:5], off offset:512
	s_nop 0
	global_load_dwordx4 v[4:7], v[4:5], off offset:2560
	v_addc_co_u32_e32 v29, vcc, 0, v25, vcc
	global_load_dwordx4 v[8:11], v[12:13], off offset:512
	s_nop 0
	global_load_dwordx4 v[12:15], v[12:13], off offset:2560
	s_nop 0
	global_load_dwordx4 v[16:19], v[20:21], off offset:512
	s_nop 0
	global_load_dwordx4 v[20:23], v[20:21], off offset:2560
	s_nop 0
	global_load_dwordx4 v[24:27], v[28:29], off offset:512
	s_nop 0
	global_load_dwordx4 v[28:31], v[28:29], off offset:2560
	s_mov_b32 s34, s23
.Lmy_moba_660:
	s_and_b32 s30, s22, s30
	s_xor_b64 s[22:23], s[6:7], -1
.LBB0_669:
	v_cndmask_b32_e64 v168, 0, 1, s[10:11]
	s_andn2_b64 vcc, exec, s[20:21]
	s_xor_b32 s31, s31, 1
	s_waitcnt lgkmcnt(0)
	s_barrier
	s_cbranch_vccz .LBB0_493
	s_mov_b64 s[10:11], s[22:23]
	s_mov_b32 s38, s35
	v_mov_b32_e32 v166, v144
	v_mov_b32_e32 v167, v169
	v_mov_b32_e32 v48, v108
	v_mov_b32_e32 v49, v109
	v_mov_b32_e32 v50, v110
	v_mov_b32_e32 v51, v111
	v_mov_b32_e32 v52, v104
	v_mov_b32_e32 v53, v105
	v_mov_b32_e32 v54, v106
	v_mov_b32_e32 v55, v107
	v_mov_b32_e32 v56, v100
	v_mov_b32_e32 v57, v101
	v_mov_b32_e32 v58, v102
	v_mov_b32_e32 v59, v103
	v_mov_b32_e32 v60, v96
	v_mov_b32_e32 v61, v97
	v_mov_b32_e32 v62, v98
	v_mov_b32_e32 v63, v99
	v_mov_b32_e32 v64, v92
	v_mov_b32_e32 v65, v93
	v_mov_b32_e32 v66, v94
	v_mov_b32_e32 v67, v95
	v_mov_b32_e32 v68, v84
	v_mov_b32_e32 v69, v85
	v_mov_b32_e32 v70, v86
	v_mov_b32_e32 v71, v87
	v_mov_b32_e32 v72, v88
	v_mov_b32_e32 v73, v89
	v_mov_b32_e32 v74, v90
	v_mov_b32_e32 v75, v91
	v_mov_b32_e32 v76, v80
	v_mov_b32_e32 v77, v81
	v_mov_b32_e32 v78, v82
	v_mov_b32_e32 v79, v83
	s_branch .LBB0_656

; DEVI f32x4 mfma16(bf16x8 a, bf16x8 b, f32x4 c) { return __builtin_amdgcn_mfma_f32_16x16x32_bf16(a, b, c, 0, 0, 0); }
; DEVI float xq_max(float v) { v = fmaxf(v, __shfl_xor(v, 16)); v = fmaxf(v, __shfl_xor(v, 32)); return v; }
; DEVI void swa_item(const Params& p, int l, int item) {
;     ...
;     float sc[10][4];
;     float mx = -INFINITY;
; #pragma unroll
;     for (int kt = 0; kt < 10; ++kt) {
;       int tile = ts + kt;
;       f32x4 acc = {0.f, 0.f, 0.f, 0.f};
;       acc = mfma16(*(const bf16x8*)(Ks + (tile * 16 + fr) * 72 + fq * 8), q0, acc);
;       acc = mfma16(*(const bf16x8*)(Ks + (tile * 16 + fr) * 72 + 32 + fq * 8), q1, acc);
; #pragma unroll
;       for (int j = 0; j < 4; ++j) {
;         int kpos = tile * 16 + fq * 4 + j;
;         bool valid = (kpos <= qpos) && (kpos > qpos - 128) && (blk > 0 || kpos >= 128);
;         float s = valid ? acc[j] * 0.125f : -INFINITY;
;         sc[kt][j] = s;
;         mx = fmaxf(mx, s);
;       }
;     }
;     mx = xq_max(mx);
;     const float sink = p.swa_sinks[l * 16 + h];
;     mx = fmaxf(mx, sink);
.LBB0_725:
	s_waitcnt lgkmcnt(14)
	v_mfma_f32_16x16x32_bf16 v[96:99], v[0:3], v[88:91], 0
	v_mfma_f32_16x16x32_bf16 v[96:99], v[4:7], v[92:95], v[96:99]
	s_waitcnt lgkmcnt(11)
	v_mfma_f32_16x16x32_bf16 v[156:159], v[32:35], v[88:91], 0
	s_waitcnt lgkmcnt(10)
	v_mfma_f32_16x16x32_bf16 v[156:159], v[36:39], v[92:95], v[156:159]
	s_nop 3
	v_mul_f32_e32 v97, 0x3e000000, v97
	v_mul_f32_e32 v96, 0x3e000000, v96
	v_cndmask_b32_e64 v97, v233, v97, s[4:5]
	v_cndmask_b32_e64 v96, v233, v96, s[52:53]
	v_cndmask_b32_e64 v97, v97, v233, s[6:7]
	v_mul_f32_e32 v98, 0x3e000000, v98
	v_mul_f32_e32 v99, 0x3e000000, v99
	v_max3_f32 v100, v96, s95, v97
	v_cndmask_b32_e64 v98, v233, v98, s[54:55]
	v_cndmask_b32_e64 v99, v233, v99, s[56:57]
	v_max3_f32 v104, v100, v98, v99
	v_mfma_f32_16x16x32_bf16 v[100:103], v[8:11], v[88:91], 0
	v_mfma_f32_16x16x32_bf16 v[144:147], v[12:15], v[92:95], v[100:103]
	s_waitcnt lgkmcnt(5)
	v_mfma_f32_16x16x32_bf16 v[166:169], v[56:59], v[88:91], 0
	s_waitcnt lgkmcnt(4)
	v_mfma_f32_16x16x32_bf16 v[166:169], v[60:63], v[92:95], v[166:169]
	s_nop 3
	v_mul_f32_e32 v100, 0x3e000000, v144
	v_mul_f32_e32 v101, 0x3e000000, v146
	v_cndmask_b32_e64 v106, v233, v100, s[58:59]
	v_mul_f32_e32 v100, 0x3e000000, v145
	v_cndmask_b32_e64 v103, v233, v101, s[60:61]
	v_mul_f32_e32 v101, 0x3e000000, v147
	v_mfma_f32_16x16x32_bf16 v[144:147], v[16:19], v[88:91], 0
	v_cndmask_b32_e64 v100, v233, v100, s[4:5]
	v_cndmask_b32_e64 v105, v100, v233, s[8:9]
	v_max3_f32 v100, v104, v106, v105
	v_mfma_f32_16x16x32_bf16 v[144:147], v[20:23], v[92:95], v[144:147]
	v_cndmask_b32_e64 v101, v233, v101, s[62:63]
	v_max3_f32 v100, v100, v103, v101
	s_nop 5
	v_mul_f32_e32 v102, 0x3e000000, v144
	v_cndmask_b32_e64 v107, v233, v102, s[10:11]
	v_mul_f32_e32 v102, 0x3e000000, v145
	v_cndmask_b32_e64 v104, v233, v102, s[12:13]
	v_max3_f32 v130, v100, v107, v104
	v_mul_f32_e32 v100, 0x3e000000, v146
	v_cndmask_b32_e64 v102, v233, v100, s[14:15]
	v_mul_f32_e32 v100, 0x3e000000, v147
	v_mfma_f32_16x16x32_bf16 v[144:147], v[24:27], v[88:91], 0
	v_cndmask_b32_e64 v100, v233, v100, s[16:17]
	v_max3_f32 v130, v130, v102, v100
	v_mfma_f32_16x16x32_bf16 v[144:147], v[28:31], v[92:95], v[144:147]
	s_nop 7
	v_mul_f32_e32 v143, 0x3e000000, v144
	v_cndmask_b32_e64 v154, v233, v143, s[18:19]
	v_mul_f32_e32 v143, 0x3e000000, v145
	v_cndmask_b32_e64 v151, v233, v143, s[20:21]
	v_mul_f32_e32 v143, 0x3e000000, v146
	v_cndmask_b32_e64 v149, v233, v143, s[22:23]
	v_mul_f32_e32 v143, 0x3e000000, v147
	v_cndmask_b32_e64 v147, v233, v143, s[24:25]
	v_mul_f32_e32 v143, 0x3e000000, v156
	v_cndmask_b32_e64 v153, v233, v143, s[26:27]
	v_mul_f32_e32 v143, 0x3e000000, v157
	v_cndmask_b32_e64 v150, v233, v143, s[28:29]
	v_mul_f32_e32 v143, 0x3e000000, v158
	v_cndmask_b32_e64 v148, v233, v143, s[30:31]
	v_mul_f32_e32 v143, 0x3e000000, v159
	v_mfma_f32_16x16x32_bf16 v[156:159], v[40:43], v[88:91], 0
	v_cndmask_b32_e64 v146, v233, v143, s[34:35]
	v_max3_f32 v130, v130, v154, v151
	v_max3_f32 v130, v130, v149, v147
	v_mfma_f32_16x16x32_bf16 v[156:159], v[44:47], v[92:95], v[156:159]
	v_max3_f32 v130, v130, v153, v150
	v_max3_f32 v130, v130, v148, v146
	s_nop 5
	v_mul_f32_e32 v143, 0x3e000000, v156
	v_cndmask_b32_e64 v165, v233, v143, s[36:37]
	v_mul_f32_e32 v143, 0x3e000000, v157
	v_cndmask_b32_e64 v164, v233, v143, s[38:39]
	v_mul_f32_e32 v143, 0x3e000000, v158
	v_cndmask_b32_e64 v163, v233, v143, s[40:41]
	v_mul_f32_e32 v143, 0x3e000000, v159
	v_mfma_f32_16x16x32_bf16 v[156:159], v[48:51], v[88:91], 0
	v_cndmask_b32_e64 v162, v233, v143, s[42:43]
	v_max3_f32 v130, v130, v165, v164
	v_max3_f32 v130, v130, v163, v162
	v_mfma_f32_16x16x32_bf16 v[158:161], v[52:55], v[92:95], v[156:159]
	s_nop 7
	v_mul_f32_e32 v143, 0x3e000000, v158
	v_cndmask_b32_e64 v158, v233, v143, s[44:45]
	v_mul_f32_e32 v143, 0x3e000000, v159
	v_cndmask_b32_e64 v156, v233, v143, s[46:47]
	v_mul_f32_e32 v143, 0x3e000000, v160
	v_cndmask_b32_e64 v155, v233, v143, s[48:49]
	v_mul_f32_e32 v143, 0x3e000000, v161
	v_cndmask_b32_e64 v152, v233, v143, s[50:51]
	v_mul_f32_e32 v143, 0x3e000000, v166
	v_cndmask_b32_e64 v161, v233, v143, s[64:65]
	v_mul_f32_e32 v143, 0x3e000000, v167
	v_cndmask_b32_e64 v160, v233, v143, s[66:67]
	v_mul_f32_e32 v143, 0x3e000000, v168
	v_cndmask_b32_e64 v159, v233, v143, s[68:69]
	v_mul_f32_e32 v143, 0x3e000000, v169
	s_waitcnt lgkmcnt(3)
	v_mfma_f32_16x16x32_bf16 v[166:169], v[64:67], v[88:91], 0
	v_max3_f32 v130, v130, v158, v156
	v_max3_f32 v130, v130, v155, v152
	v_cndmask_b32_e64 v157, v233, v143, s[70:71]
	s_waitcnt lgkmcnt(2)
	v_mfma_f32_16x16x32_bf16 v[166:169], v[68:71], v[92:95], v[166:169]
	v_max3_f32 v130, v130, v161, v160
	v_max3_f32 v130, v130, v159, v157
	s_waitcnt lgkmcnt(1)
	v_mfma_f32_16x16x32_bf16 v[88:91], v[72:75], v[88:91], 0
	s_waitcnt lgkmcnt(0)
	v_mfma_f32_16x16x32_bf16 v[92:95], v[76:79], v[92:95], v[88:91]
	s_nop 1
	v_mul_f32_e32 v143, 0x3e000000, v166
	v_cndmask_b32_e64 v145, v143, v233, s[72:73]
	v_mul_f32_e32 v143, 0x3e000000, v167
	v_cndmask_b32_e64 v144, v233, v143, s[74:75]
	v_max3_f32 v166, v130, v145, v144
	v_mul_f32_e32 v130, 0x3e000000, v168
	v_cndmask_b32_e64 v143, v130, v233, s[76:77]
	v_mul_f32_e32 v130, 0x3e000000, v169
	v_mul_f32_e32 v88, 0x3e000000, v92
	v_cndmask_b32_e64 v130, v130, v233, s[78:79]
	v_cndmask_b32_e64 v91, v88, v233, s[80:81]
	v_mul_f32_e32 v88, 0x3e000000, v93
	v_max3_f32 v166, v166, v143, v130
	v_cndmask_b32_e64 v90, v233, v88, s[82:83]
	v_max3_f32 v92, v166, v91, v90
	v_mul_f32_e32 v88, 0x3e000000, v94
	v_cndmask_b32_e64 v89, v88, v233, s[84:85]
	v_mul_f32_e32 v88, 0x3e000000, v95
	v_cndmask_b32_e64 v88, v88, v233, s[86:87]
	v_max3_f32 v92, v92, v89, v88
	ds_bpermute_b32 v93, v131, v92
	s_waitcnt lgkmcnt(0)
	v_max_f32_e32 v93, v93, v93
	v_max_f32_e32 v92, v92, v93
	ds_bpermute_b32 v93, v132, v92
	s_cmpk_eq_i32 s2, 0x180
	s_cbranch_scc1 .Lmy_swa_w0
	s_waitcnt vmcnt(6) lgkmcnt(0)
	s_branch .Lmy_swa_wd

; DEVI void swa_item(const Params& p, int l, int item) {
;     ...
;     mx = fmaxf(mx, sink);
;     float sum = 0.f;
;     bf16x8 pk[5];
; #pragma unroll
;     for (int pp = 0; pp < 5; ++pp) {
;       float e[8];
; #pragma unroll
;       for (int j = 0; j < 4; ++j) {
;         e[j] = __expf(sc[2 * pp][j] - mx);
;         e[4 + j] = __expf(sc[2 * pp + 1][j] - mx);
;       }
; #pragma unroll
;       for (int j = 0; j < 8; ++j) { sum += e[j]; pk[pp][j] = (short)f2bf(e[j]); }
;     }
.Lmy_swa_wd:
	v_max3_f32 v167, v92, v93, v170
	v_sub_f32_e32 v92, v96, v167
	v_mul_f32_e32 v92, 0x3fb8aa3b, v92
	v_sub_f32_e32 v94, v97, v167
	v_exp_f32_e32 v92, v92
	v_mul_f32_e32 v94, 0x3fb8aa3b, v94
	v_sub_f32_e32 v95, v98, v167
	v_exp_f32_e32 v96, v94
	v_mul_f32_e32 v95, 0x3fb8aa3b, v95
	v_sub_f32_e32 v98, v99, v167
	v_sub_f32_e32 v93, v106, v167
	v_exp_f32_e32 v97, v95
	v_mul_f32_e32 v98, 0x3fb8aa3b, v98
	v_mul_f32_e32 v93, 0x3fb8aa3b, v93
	v_sub_f32_e32 v94, v105, v167
	v_exp_f32_e32 v98, v98
	v_exp_f32_e32 v93, v93
	v_mul_f32_e32 v94, 0x3fb8aa3b, v94
	v_sub_f32_e32 v99, v101, v167
	v_add_f32_e32 v101, 0, v92
	v_exp_f32_e32 v94, v94
	v_add_f32_e32 v101, v96, v101
	v_sub_f32_e32 v95, v103, v167
	v_add_f32_e32 v101, v97, v101
	v_mul_f32_e32 v95, 0x3fb8aa3b, v95
	v_add_f32_e32 v101, v98, v101
	v_exp_f32_e32 v95, v95
	v_mul_f32_e32 v99, 0x3fb8aa3b, v99
	v_add_f32_e32 v101, v93, v101
	v_cvt_pk_bf16_f32 v92, v92, v96
	v_sub_f32_e32 v96, v107, v167
	v_exp_f32_e32 v99, v99
	v_add_f32_e32 v101, v94, v101
	v_cvt_pk_bf16_f32 v94, v93, v94
	v_cvt_pk_bf16_f32 v93, v97, v98
	v_mul_f32_e32 v96, 0x3fb8aa3b, v96
	v_sub_f32_e32 v98, v104, v167
	v_exp_f32_e32 v96, v96
	v_mul_f32_e32 v98, 0x3fb8aa3b, v98
	v_sub_f32_e32 v102, v102, v167
	v_exp_f32_e32 v98, v98
	v_mul_f32_e32 v102, 0x3fb8aa3b, v102
	v_sub_f32_e32 v100, v100, v167
	v_add_f32_e32 v101, v95, v101
	v_sub_f32_e32 v97, v154, v167
	v_exp_f32_e32 v104, v102
	v_mul_f32_e32 v100, 0x3fb8aa3b, v100
	v_add_f32_e32 v101, v99, v101
	v_cvt_pk_bf16_f32 v95, v95, v99
	v_mul_f32_e32 v97, 0x3fb8aa3b, v97
	v_sub_f32_e32 v99, v151, v167
	v_exp_f32_e32 v100, v100
	v_exp_f32_e32 v97, v97
	v_mul_f32_e32 v99, 0x3fb8aa3b, v99
	v_sub_f32_e32 v102, v149, v167
	v_add_f32_e32 v101, v96, v101
	v_exp_f32_e32 v99, v99
	v_mul_f32_e32 v102, 0x3fb8aa3b, v102
	v_sub_f32_e32 v103, v147, v167
	v_add_f32_e32 v101, v98, v101
	v_exp_f32_e32 v102, v102
	v_mul_f32_e32 v103, 0x3fb8aa3b, v103
	v_add_f32_e32 v101, v104, v101
	v_exp_f32_e32 v103, v103
	v_add_f32_e32 v101, v100, v101
	v_add_f32_e32 v101, v97, v101
	v_add_f32_e32 v101, v99, v101
	v_add_f32_e32 v101, v102, v101
	v_add_f32_e32 v105, v103, v101
	v_cvt_pk_bf16_f32 v101, v104, v100
	v_cvt_pk_bf16_f32 v100, v96, v98
	v_sub_f32_e32 v96, v153, v167
	v_mul_f32_e32 v96, 0x3fb8aa3b, v96
	v_sub_f32_e32 v98, v150, v167
	v_cvt_pk_bf16_f32 v103, v102, v103
	v_cvt_pk_bf16_f32 v102, v97, v99
	v_exp_f32_e32 v96, v96
	v_mul_f32_e32 v98, 0x3fb8aa3b, v98
	v_sub_f32_e32 v99, v148, v167
	v_exp_f32_e32 v104, v98
	v_mul_f32_e32 v99, 0x3fb8aa3b, v99
	v_sub_f32_e32 v107, v146, v167
	v_sub_f32_e32 v97, v165, v167
	v_exp_f32_e32 v106, v99
	v_mul_f32_e32 v107, 0x3fb8aa3b, v107
	v_mul_f32_e32 v97, 0x3fb8aa3b, v97
	v_sub_f32_e32 v98, v164, v167
	v_exp_f32_e32 v107, v107
	v_exp_f32_e32 v97, v97
	v_mul_f32_e32 v98, 0x3fb8aa3b, v98
	v_sub_f32_e32 v99, v163, v167
	v_add_f32_e32 v105, v96, v105
	v_exp_f32_e32 v98, v98
	v_mul_f32_e32 v99, 0x3fb8aa3b, v99
	v_sub_f32_e32 v146, v162, v167
	v_add_f32_e32 v105, v104, v105
	v_exp_f32_e32 v99, v99
	v_mul_f32_e32 v146, 0x3fb8aa3b, v146
	v_add_f32_e32 v105, v106, v105
	v_exp_f32_e32 v146, v146
	v_add_f32_e32 v105, v107, v105
	v_add_f32_e32 v105, v97, v105
	v_add_f32_e32 v105, v98, v105
	v_cvt_pk_bf16_f32 v98, v97, v98
	v_cvt_pk_bf16_f32 v97, v106, v107
	v_sub_f32_e32 v107, v156, v167
	v_add_f32_e32 v105, v99, v105
	v_mul_f32_e32 v107, 0x3fb8aa3b, v107
	v_add_f32_e32 v105, v146, v105
	v_cvt_pk_bf16_f32 v99, v99, v146
	v_cvt_pk_bf16_f32 v96, v96, v104
	v_sub_f32_e32 v104, v158, v167
	v_exp_f32_e32 v146, v107
	v_sub_f32_e32 v107, v160, v167
	v_mul_f32_e32 v104, 0x3fb8aa3b, v104
	v_mul_f32_e32 v107, 0x3fb8aa3b, v107
	v_exp_f32_e32 v104, v104
	v_exp_f32_e32 v147, v107
	v_sub_f32_e32 v107, v155, v167
	v_mul_f32_e32 v107, 0x3fb8aa3b, v107
	v_sub_f32_e32 v149, v152, v167
	v_sub_f32_e32 v106, v161, v167
	v_exp_f32_e32 v148, v107
	v_mul_f32_e32 v149, 0x3fb8aa3b, v149
	v_mul_f32_e32 v106, 0x3fb8aa3b, v106
	v_exp_f32_e32 v149, v149
	v_sub_f32_e32 v91, v91, v167
	v_exp_f32_e32 v106, v106
	v_sub_f32_e32 v107, v159, v167
	v_add_f32_e32 v105, v104, v105
	v_mul_f32_e32 v91, 0x3fb8aa3b, v91
	v_mul_f32_e32 v107, 0x3fb8aa3b, v107
	v_sub_f32_e32 v150, v157, v167
	v_add_f32_e32 v105, v146, v105
	v_cvt_pk_bf16_f32 v104, v104, v146
	v_exp_f32_e32 v146, v91
	v_sub_f32_e32 v91, v144, v167
	v_exp_f32_e32 v107, v107
	v_mul_f32_e32 v150, 0x3fb8aa3b, v150
	v_add_f32_e32 v105, v148, v105
	v_sub_f32_e32 v145, v145, v167
	v_mul_f32_e32 v91, 0x3fb8aa3b, v91
	v_exp_f32_e32 v150, v150
	v_add_f32_e32 v105, v149, v105
	v_mul_f32_e32 v145, 0x3fb8aa3b, v145
	v_exp_f32_e32 v144, v91
	v_sub_f32_e32 v91, v143, v167
	v_add_f32_e32 v105, v106, v105
	v_exp_f32_e32 v145, v145
	v_mul_f32_e32 v91, 0x3fb8aa3b, v91
	v_add_f32_e32 v105, v147, v105
	v_exp_f32_e32 v143, v91
	v_sub_f32_e32 v91, v130, v167
	v_add_f32_e32 v105, v107, v105
	v_mul_f32_e32 v91, 0x3fb8aa3b, v91
	v_add_f32_e32 v151, v150, v105
	v_sub_f32_e32 v90, v90, v167
	v_exp_f32_e32 v130, v91
	v_mul_f32_e32 v90, 0x3fb8aa3b, v90
	v_sub_f32_e32 v89, v89, v167
	v_add_f32_e32 v91, v145, v151
	v_exp_f32_e32 v90, v90
	v_mul_f32_e32 v89, 0x3fb8aa3b, v89
	v_sub_f32_e32 v88, v88, v167
	v_add_f32_e32 v91, v144, v91
	v_exp_f32_e32 v89, v89
	v_mul_f32_e32 v88, 0x3fb8aa3b, v88
	v_add_f32_e32 v91, v143, v91
	v_exp_f32_e32 v88, v88
	v_add_f32_e32 v91, v130, v91
	v_add_f32_e32 v91, v146, v91
	v_add_f32_e32 v91, v90, v91
	v_add_f32_e32 v91, v89, v91
	v_cvt_pk_bf16_f32 v106, v106, v147
	v_add_f32_e32 v147, v88, v91
	v_cvt_pk_bf16_f32 v91, v89, v88
	v_cvt_pk_bf16_f32 v89, v143, v130
	ds_bpermute_b32 v130, v131, v147
	v_cvt_pk_bf16_f32 v90, v146, v90
	v_cvt_pk_bf16_f32 v88, v145, v144
	v_cvt_pk_bf16_f32 v107, v107, v150
	v_cvt_pk_bf16_f32 v105, v148, v149
	s_waitcnt lgkmcnt(0)
; DEVI float bfs(short h) { return __uint_as_float(((unsigned)(u16)h) << 16); }
; DEVI bf16x8 cat8(bf16x4 a, bf16x4 b) { return __builtin_shufflevector(a, b, 0, 1, 2, 3, 4, 5, 6, 7); }
; DEVI f32x4 mfma16(bf16x8 a, bf16x8 b, f32x4 c) { return __builtin_amdgcn_mfma_f32_16x16x32_bf16(a, b, c, 0, 0, 0); }
; DEVI float silu_f(float x) { return x * __builtin_amdgcn_rcpf(1.f + __expf(-x)); }
; DEVI float xq_sum(float v) { v += __shfl_xor(v, 16); v += __shfl_xor(v, 32); return v; }
; DEVI void swa_item(const Params& p, int l, int item) {
;     ...
;     sum = xq_sum(sum);
;     const float inv = __builtin_amdgcn_rcpf(sum + __expf(sink - mx));
; #pragma unroll
;     for (int ct = 0; ct < 4; ++ct) {
;       f32x4 acc = {0.f, 0.f, 0.f, 0.f};
; #pragma unroll
;       for (int pp = 0; pp < 5; ++pp) {
;         bf16x4 a0 = tr_read(Vs + ((ts + 2 * pp) * 16 + fq * 4 + trr) * 80 + ct * 16 + trc * 4);
;         bf16x4 a1 = tr_read(Vs + ((ts + 2 * pp + 1) * 16 + fq * 4 + trr) * 80 + ct * 16 + trc * 4);
;         acc = mfma16(cat8(a0, a1), pk[pp], acc);
;       }
;       int dv = ct * 16 + fq * 4;
;       const bf16x4 gt = gcur[ct];
;       *(bf16x4*)(p.ys + (long)1 * T_ * 1024 + qtok * 1024 + h * 64 + dv) =
;           pack4(acc[0] * inv * silu_f(bfs(gt[0])), acc[1] * inv * silu_f(bfs(gt[1])),
;                 acc[2] * inv * silu_f(bfs(gt[2])), acc[3] * inv * silu_f(bfs(gt[3])));
	v_add_f32_e32 v130, v147, v130
	ds_read_b64_tr_b16 v[144:145], v133 offset:36864
	ds_read_b64_tr_b16 v[146:147], v134 offset:36864
	ds_read_b64_tr_b16 v[148:149], v135 offset:36864
	ds_read_b64_tr_b16 v[150:151], v136 offset:36864
	s_waitcnt lgkmcnt(2)
	v_mfma_f32_16x16x32_bf16 v[144:147], v[144:147], v[92:95], 0
	ds_bpermute_b32 v143, v132, v130
	s_waitcnt lgkmcnt(0)
	v_add_f32_e32 v130, v130, v143
	v_mfma_f32_16x16x32_bf16 v[144:147], v[148:151], v[100:103], v[144:147]
	ds_read_b64_tr_b16 v[148:149], v137 offset:36864
	ds_read_b64_tr_b16 v[150:151], v138 offset:36864
	v_sub_f32_e32 v143, v170, v167
	v_mul_f32_e32 v143, 0x3fb8aa3b, v143
	s_waitcnt lgkmcnt(0)
	v_mfma_f32_16x16x32_bf16 v[144:147], v[148:151], v[96:99], v[144:147]
	ds_read_b64_tr_b16 v[148:149], v139 offset:36864
	ds_read_b64_tr_b16 v[150:151], v140 offset:36864
	v_exp_f32_e32 v143, v143
	s_waitcnt lgkmcnt(0)
	v_mfma_f32_16x16x32_bf16 v[144:147], v[148:151], v[104:107], v[144:147]
	ds_read_b64_tr_b16 v[148:149], v141 offset:36864
	ds_read_b64_tr_b16 v[150:151], v142 offset:36864
	v_add_f32_e32 v130, v143, v130
	v_rcp_f32_e32 v130, v130
	s_waitcnt lgkmcnt(0)
	v_mfma_f32_16x16x32_bf16 v[144:147], v[148:151], v[88:91], v[144:147]
	v_lshlrev_b32_e32 v148, 16, v128
	v_and_b32_e32 v149, 0xffff0000, v128
	v_mul_f32_e32 v128, 0xbfb8aa3b, v148
	v_exp_f32_e32 v128, v128
	s_nop 3
	v_pk_mul_f32 v[144:145], v[144:145], v[130:131] op_sel_hi:[1,0]
	v_pk_mul_f32 v[146:147], v[146:147], v[130:131] op_sel_hi:[1,0]
	v_add_f32_e32 v128, 1.0, v128
	v_rcp_f32_e32 v150, v128
	v_mul_f32_e32 v128, 0xbfb8aa3b, v149
	v_exp_f32_e32 v128, v128
	s_nop 0
	v_add_f32_e32 v128, 1.0, v128
	v_rcp_f32_e32 v151, v128
	s_nop 0
	v_pk_mul_f32 v[148:149], v[150:151], v[148:149]
	s_nop 0
	v_pk_mul_f32 v[144:145], v[148:149], v[144:145]
	v_and_b32_e32 v149, 0xffff0000, v129
	v_lshlrev_b32_e32 v148, 16, v129
	v_mul_f32_e32 v128, 0xbfb8aa3b, v148
	v_mul_f32_e32 v129, 0xbfb8aa3b, v149
	v_exp_f32_e32 v128, v128
	v_exp_f32_e32 v129, v129
	v_cvt_pk_bf16_f32 v144, v144, v145
	v_add_f32_e32 v128, 1.0, v128
	v_add_f32_e32 v129, 1.0, v129
	v_rcp_f32_e32 v128, v128
	v_rcp_f32_e32 v129, v129
	s_nop 0
	v_pk_mul_f32 v[128:129], v[128:129], v[148:149]
	s_nop 0
	v_pk_mul_f32 v[128:129], v[128:129], v[146:147]
	s_nop 0
	v_cvt_pk_bf16_f32 v145, v128, v129
	v_lshl_add_u64 v[128:129], v[112:113], 0, s[2:3]
	global_store_dwordx2 v[128:129], v[144:145], off offset:-64
	ds_read_b64_tr_b16 v[144:145], v133 offset:36896
	ds_read_b64_tr_b16 v[146:147], v134 offset:36896
	ds_read_b64_tr_b16 v[148:149], v135 offset:36896
	ds_read_b64_tr_b16 v[150:151], v136 offset:36896
	s_waitcnt lgkmcnt(2)
	v_mfma_f32_16x16x32_bf16 v[144:147], v[144:147], v[92:95], 0
	s_add_u32 s2, s2, 0x80
	s_addc_u32 s3, s3, 0
	s_add_u32 s88, s88, 4
	s_waitcnt lgkmcnt(0)
	v_mfma_f32_16x16x32_bf16 v[144:147], v[148:151], v[100:103], v[144:147]
	ds_read_b64_tr_b16 v[148:149], v137 offset:36896
	ds_read_b64_tr_b16 v[150:151], v138 offset:36896
	s_addc_u32 s89, s89, 0
	s_cmpk_lg_i32 s2, 0x200
	s_waitcnt lgkmcnt(0)
	v_mfma_f32_16x16x32_bf16 v[144:147], v[148:151], v[96:99], v[144:147]
	ds_read_b64_tr_b16 v[148:149], v139 offset:36896
	ds_read_b64_tr_b16 v[150:151], v140 offset:36896
	s_waitcnt lgkmcnt(0)
	v_mfma_f32_16x16x32_bf16 v[144:147], v[148:151], v[104:107], v[144:147]
	ds_read_b64_tr_b16 v[148:149], v141 offset:36896
	ds_read_b64_tr_b16 v[150:151], v142 offset:36896
	s_waitcnt lgkmcnt(0)
	v_mfma_f32_16x16x32_bf16 v[144:147], v[148:151], v[88:91], v[144:147]
	v_lshlrev_b32_e32 v148, 16, v126
	v_and_b32_e32 v149, 0xffff0000, v126
	v_mul_f32_e32 v126, 0xbfb8aa3b, v148
	v_exp_f32_e32 v126, v126
	s_nop 3
	v_pk_mul_f32 v[144:145], v[144:145], v[130:131] op_sel_hi:[1,0]
	v_pk_mul_f32 v[146:147], v[146:147], v[130:131] op_sel_hi:[1,0]
	v_add_f32_e32 v126, 1.0, v126
	v_rcp_f32_e32 v150, v126
	v_mul_f32_e32 v126, 0xbfb8aa3b, v149
	v_exp_f32_e32 v126, v126
	s_nop 0
	v_add_f32_e32 v126, 1.0, v126
	v_rcp_f32_e32 v151, v126
	s_nop 0
	v_pk_mul_f32 v[148:149], v[150:151], v[148:149]
	s_nop 0
	v_pk_mul_f32 v[144:145], v[148:149], v[144:145]
	v_and_b32_e32 v149, 0xffff0000, v127
	v_lshlrev_b32_e32 v148, 16, v127
	v_mul_f32_e32 v126, 0xbfb8aa3b, v148
	v_mul_f32_e32 v127, 0xbfb8aa3b, v149
	v_exp_f32_e32 v126, v126
	v_exp_f32_e32 v127, v127
	v_cvt_pk_bf16_f32 v144, v144, v145
	v_add_f32_e32 v126, 1.0, v126
	v_add_f32_e32 v127, 1.0, v127
	v_rcp_f32_e32 v126, v126
	v_rcp_f32_e32 v127, v127
	s_nop 0
	v_pk_mul_f32 v[126:127], v[126:127], v[148:149]
	s_nop 0
	v_pk_mul_f32 v[126:127], v[126:127], v[146:147]
	s_nop 0
	v_cvt_pk_bf16_f32 v145, v126, v127
	global_store_dwordx2 v[128:129], v[144:145], off offset:-32
	ds_read_b64_tr_b16 v[144:145], v133 offset:36928
	ds_read_b64_tr_b16 v[146:147], v134 offset:36928
	ds_read_b64_tr_b16 v[148:149], v135 offset:36928
	ds_read_b64_tr_b16 v[150:151], v136 offset:36928
	s_waitcnt lgkmcnt(2)
; DEVI float bfs(short h) { return __uint_as_float(((unsigned)(u16)h) << 16); }
; DEVI bf16x8 cat8(bf16x4 a, bf16x4 b) { return __builtin_shufflevector(a, b, 0, 1, 2, 3, 4, 5, 6, 7); }
; DEVI f32x4 mfma16(bf16x8 a, bf16x8 b, f32x4 c) { return __builtin_amdgcn_mfma_f32_16x16x32_bf16(a, b, c, 0, 0, 0); }
; DEVI float silu_f(float x) { return x * __builtin_amdgcn_rcpf(1.f + __expf(-x)); }
; DEVI void swa_item(const Params& p, int l, int item) {
;     ...
;     if (hh + 1 < 4) {
;       q0n = *(const bf16x8*)(proj + qtok * NP + C_BQ + (h + 1) * 64 + fq * 8);
;       q1n = *(const bf16x8*)(proj + qtok * NP + C_BQ + (h + 1) * 64 + 32 + fq * 8);
;       gn0 = *(const bf16x4*)(proj + qtok * NP + C_BGATE + (h + 1) * 64 + fq * 4);
;       gn1 = *(const bf16x4*)(proj + qtok * NP + C_BGATE + (h + 1) * 64 + 16 + fq * 4);
;       gn2 = *(const bf16x4*)(proj + qtok * NP + C_BGATE + (h + 1) * 64 + 32 + fq * 4);
;       gn3 = *(const bf16x4*)(proj + qtok * NP + C_BGATE + (h + 1) * 64 + 48 + fq * 4);
;     }
;     ...
;     for (int ct = 0; ct < 4; ++ct) {
;       f32x4 acc = {0.f, 0.f, 0.f, 0.f};
; #pragma unroll
;       for (int pp = 0; pp < 5; ++pp) {
;         bf16x4 a0 = tr_read(Vs + ((ts + 2 * pp) * 16 + fq * 4 + trr) * 80 + ct * 16 + trc * 4);
;         bf16x4 a1 = tr_read(Vs + ((ts + 2 * pp + 1) * 16 + fq * 4 + trr) * 80 + ct * 16 + trc * 4);
;         acc = mfma16(cat8(a0, a1), pk[pp], acc);
;       }
;       int dv = ct * 16 + fq * 4;
;       const bf16x4 gt = gcur[ct];
;       *(bf16x4*)(p.ys + (long)1 * T_ * 1024 + qtok * 1024 + h * 64 + dv) =
;           pack4(acc[0] * inv * silu_f(bfs(gt[0])), acc[1] * inv * silu_f(bfs(gt[1])),
;                 acc[2] * inv * silu_f(bfs(gt[2])), acc[3] * inv * silu_f(bfs(gt[3])));
	v_mfma_f32_16x16x32_bf16 v[144:147], v[144:147], v[92:95], 0
	v_lshlrev_b32_e32 v126, 16, v114
	v_and_b32_e32 v127, 0xffff0000, v114
	v_mul_f32_e32 v114, 0xbfb8aa3b, v126
	s_waitcnt lgkmcnt(0)
	v_mfma_f32_16x16x32_bf16 v[144:147], v[148:151], v[100:103], v[144:147]
	ds_read_b64_tr_b16 v[148:149], v137 offset:36928
	ds_read_b64_tr_b16 v[150:151], v138 offset:36928
	v_exp_f32_e32 v114, v114
	s_waitcnt lgkmcnt(0)
	v_mfma_f32_16x16x32_bf16 v[144:147], v[148:151], v[96:99], v[144:147]
	ds_read_b64_tr_b16 v[148:149], v139 offset:36928
	ds_read_b64_tr_b16 v[150:151], v140 offset:36928
	v_add_f32_e32 v114, 1.0, v114
	s_waitcnt lgkmcnt(0)
	v_mfma_f32_16x16x32_bf16 v[144:147], v[148:151], v[104:107], v[144:147]
	ds_read_b64_tr_b16 v[148:149], v141 offset:36928
	ds_read_b64_tr_b16 v[150:151], v142 offset:36928
	s_waitcnt lgkmcnt(0)
	v_mfma_f32_16x16x32_bf16 v[144:147], v[148:151], v[88:91], v[144:147]
	v_rcp_f32_e32 v148, v114
	v_mul_f32_e32 v114, 0xbfb8aa3b, v127
	v_exp_f32_e32 v114, v114
	s_nop 4
	v_pk_mul_f32 v[144:145], v[144:145], v[130:131] op_sel_hi:[1,0]
	v_pk_mul_f32 v[146:147], v[146:147], v[130:131] op_sel_hi:[1,0]
	v_add_f32_e32 v114, 1.0, v114
	v_rcp_f32_e32 v149, v114
	s_nop 0
	v_pk_mul_f32 v[126:127], v[148:149], v[126:127]
	s_nop 0
	v_pk_mul_f32 v[126:127], v[126:127], v[144:145]
	v_and_b32_e32 v145, 0xffff0000, v115
	v_lshlrev_b32_e32 v144, 16, v115
	v_mul_f32_e32 v114, 0xbfb8aa3b, v144
	v_mul_f32_e32 v115, 0xbfb8aa3b, v145
	v_exp_f32_e32 v114, v114
	v_exp_f32_e32 v115, v115
	v_cvt_pk_bf16_f32 v126, v126, v127
	v_add_f32_e32 v114, 1.0, v114
	v_add_f32_e32 v115, 1.0, v115
	v_rcp_f32_e32 v114, v114
	v_rcp_f32_e32 v115, v115
	s_nop 0
	v_pk_mul_f32 v[114:115], v[114:115], v[144:145]
	s_nop 0
	v_pk_mul_f32 v[114:115], v[114:115], v[146:147]
	s_nop 0
	v_cvt_pk_bf16_f32 v127, v114, v115
	global_store_dwordx2 v[128:129], v[126:127], off
	ds_read_b64_tr_b16 v[144:145], v133 offset:36960
	ds_read_b64_tr_b16 v[146:147], v134 offset:36960
	s_waitcnt lgkmcnt(0)
	v_mfma_f32_16x16x32_bf16 v[92:95], v[144:147], v[92:95], 0
	ds_read_b64_tr_b16 v[144:145], v135 offset:36960
	ds_read_b64_tr_b16 v[146:147], v136 offset:36960
	s_waitcnt vmcnt(3)
	v_mov_b64_e32 v[126:127], v[122:123]
	v_mov_b64_e32 v[114:115], v[120:121]
	s_waitcnt lgkmcnt(0)
	v_mfma_f32_16x16x32_bf16 v[92:95], v[144:147], v[100:103], v[92:95]
	ds_read_b64_tr_b16 v[100:101], v137 offset:36960
	ds_read_b64_tr_b16 v[102:103], v138 offset:36960
	s_waitcnt lgkmcnt(0)
	v_mfma_f32_16x16x32_bf16 v[92:95], v[100:103], v[96:99], v[92:95]
	ds_read_b64_tr_b16 v[96:97], v139 offset:36960
	ds_read_b64_tr_b16 v[98:99], v140 offset:36960
	s_waitcnt lgkmcnt(0)
	v_mfma_f32_16x16x32_bf16 v[92:95], v[96:99], v[104:107], v[92:95]
	ds_read_b64_tr_b16 v[96:97], v141 offset:36960
	ds_read_b64_tr_b16 v[98:99], v142 offset:36960
	s_waitcnt lgkmcnt(0)
	v_mfma_f32_16x16x32_bf16 v[88:91], v[96:99], v[88:91], v[92:95]
	s_nop 3
	v_and_b32_e32 v93, 0xffff0000, v108
	v_lshlrev_b32_e32 v92, 16, v108
	v_mul_f32_e32 v94, 0xbfb8aa3b, v92
	v_mul_f32_e32 v95, 0xbfb8aa3b, v93
	v_exp_f32_e32 v94, v94
	v_exp_f32_e32 v95, v95
	v_pk_mul_f32 v[88:89], v[130:131], v[88:89] op_sel_hi:[0,1]
	v_pk_mul_f32 v[90:91], v[130:131], v[90:91] op_sel_hi:[0,1]
	v_add_f32_e32 v94, 1.0, v94
	v_add_f32_e32 v95, 1.0, v95
	v_rcp_f32_e32 v94, v94
	v_rcp_f32_e32 v95, v95
	s_nop 0
	v_pk_mul_f32 v[92:93], v[94:95], v[92:93]
	s_nop 0
	v_pk_mul_f32 v[88:89], v[92:93], v[88:89]
	v_and_b32_e32 v93, 0xffff0000, v109
	v_lshlrev_b32_e32 v92, 16, v109
	v_mul_f32_e32 v94, 0xbfb8aa3b, v92
	v_mul_f32_e32 v95, 0xbfb8aa3b, v93
	v_exp_f32_e32 v94, v94
	v_exp_f32_e32 v95, v95
	v_cvt_pk_bf16_f32 v88, v88, v89
	v_mov_b64_e32 v[108:109], v[118:119]
	v_add_f32_e32 v94, 1.0, v94
	v_add_f32_e32 v95, 1.0, v95
	v_rcp_f32_e32 v94, v94
	v_rcp_f32_e32 v95, v95
	s_nop 0
	v_pk_mul_f32 v[92:93], v[94:95], v[92:93]
	s_nop 0
	v_pk_mul_f32 v[90:91], v[92:93], v[90:91]
	v_mov_b64_e32 v[94:95], v[82:83]
	v_cvt_pk_bf16_f32 v89, v90, v91
	global_store_dwordx2 v[128:129], v[88:89], off offset:32
	v_mov_b64_e32 v[90:91], v[86:87]
	v_mov_b64_e32 v[88:89], v[84:85]
	v_mov_b64_e32 v[92:93], v[80:81]
	v_mov_b64_e32 v[128:129], v[124:125]
	s_cbranch_scc0 .LBB0_728
.LBB0_726:
	global_load_dword v170, v211, s[88:89]
	s_cmpk_eq_i32 s2, 0x180
	s_cbranch_scc1 .LBB0_725
	v_lshl_add_u64 v[80:81], v[110:111], 0, s[2:3]
	v_add_co_u32_e32 v80, vcc, 0x16801000, v80
	v_lshl_add_u64 v[96:97], v[116:117], 0, s[2:3]
	s_nop 0
	v_addc_co_u32_e32 v81, vcc, 0, v81, vcc
	global_load_dwordx4 v[84:87], v[80:81], off offset:2176
	s_nop 0
	global_load_dwordx4 v[80:83], v[80:81], off offset:2240
	s_nop 0
	global_load_dwordx2 v[124:125], v[96:97], off offset:-64
	global_load_dwordx2 v[122:123], v[96:97], off offset:-32
	global_load_dwordx2 v[120:121], v[96:97], off
	global_load_dwordx2 v[118:119], v[96:97], off offset:32
	s_branch .LBB0_725
